# UP epilogue shuffles via DPP row rotate and permlane swaps, WIN epilogue xor reductions via permlane swaps, barrier leader reorder
# speedup vs baseline: 1.0045x; 1.0045x over previous
.LBB0_455:
	s_lshl_b32 s1, s0, 8
	s_cmp_lg_u32 s0, 8
	s_cselect_b32 s1, s1, 0x300
	v_lshlrev_b32_e32 v166, 3, v161
	s_or_b32 s1, s1, s15
	v_or_b32_e32 v166, s1, v166
	s_lshl_b32 s1, s62, 8
	v_cmp_eq_u32_e64 s[40:41], 0, v161
	v_add_u32_e32 v161, s1, v165
	v_lshlrev_b32_e32 v166, 1, v166
	v_lshl_add_u32 v168, v161, 12, v166
	v_mul_lo_u32 v161, v161, 20
	s_waitcnt lgkmcnt(0)
	v_pk_fma_f32 v[146:147], v[146:147], v[160:161], v[110:111] op_sel_hi:[1,0,1]
	v_pk_fma_f32 v[144:145], v[144:145], v[160:161], v[108:109] op_sel_hi:[1,0,1]
	v_pk_fma_f32 v[142:143], v[142:143], v[160:161], v[102:103] op_sel_hi:[1,0,1]
	v_pk_fma_f32 v[140:141], v[140:141], v[160:161], v[100:101] op_sel_hi:[1,0,1]
	s_cmp_lt_i32 s0, 3
	v_or_b32_e32 v167, s13, v161
	v_cvt_pk_bf16_f32 v170, v144, v145
	v_cvt_pk_bf16_f32 v171, v146, v147
	v_cvt_pk_bf16_f32 v172, v140, v141
	v_cvt_pk_bf16_f32 v173, v142, v143
	s_cselect_b64 s[44:45], -1, 0
	s_cmp_gt_i32 s0, 2
	global_store_dwordx4 v168, v[170:173], s[92:93]
	s_cbranch_scc1 .LBB0_459
	v_mul_f32_e32 v145, v145, v145
	v_fmac_f32_e32 v145, v144, v144
	v_mul_f32_e32 v144, v147, v147
	v_fmac_f32_e32 v144, v146, v146
	v_mul_f32_e32 v141, v141, v141
	v_add_f32_e32 v144, v145, v144
	v_fmac_f32_e32 v141, v140, v140
	v_add_f32_e32 v140, v141, v144
	v_mul_f32_e32 v141, v143, v143
	v_fmac_f32_e32 v141, v142, v142
	v_and_b32_e32 v142, 64, v1
	v_add_f32_e32 v140, v141, v140
	v_add_u32_e32 v142, 64, v142
	v_mov_b32_e32 v141, v140
	s_nop 1
	v_permlane16_swap_b32_e32 v140, v141
	s_waitcnt lgkmcnt(0)
	v_add_f32_e32 v140, v140, v141
	v_mov_b32_e32 v141, v140
	s_nop 1
	v_permlane32_swap_b32_e32 v140, v141
	s_and_saveexec_b64 s[42:43], s[40:41]
	s_cbranch_execz .LBB0_458
	s_lshl_b32 s49, s0, 5
	v_lshl_add_u32 v142, v167, 2, s49
	s_waitcnt lgkmcnt(0)
	v_add_f32_e32 v140, v140, v141
	global_store_dword v142, v140, s[74:75]

.LBB0_459:
	s_lshl_b32 s42, s0, 1
	v_mov_b32_e32 v161, v160
	v_mov_b32_e32 v140, v160
	s_waitcnt lgkmcnt(0)
	v_mov_b32_e32 v141, v160
	s_or_b32 s49, s42, 1
	v_pk_fma_f32 v[138:139], v[138:139], v[140:141], v[96:97]
	v_pk_fma_f32 v[136:137], v[136:137], v[160:161], v[94:95]
	v_pk_fma_f32 v[134:135], v[134:135], v[140:141], v[92:93]
	v_pk_fma_f32 v[132:133], v[132:133], v[160:161], v[90:91]
	s_cmp_lt_i32 s49, 5
	v_cvt_pk_bf16_f32 v140, v136, v137
	v_cvt_pk_bf16_f32 v141, v138, v139
	v_cvt_pk_bf16_f32 v142, v132, v133
	v_cvt_pk_bf16_f32 v143, v134, v135
	v_or_b32_e32 v144, 0x100, v168
	s_cselect_b64 s[62:63], -1, 0
	s_cmp_gt_i32 s49, 4
	global_store_dwordx4 v144, v[140:143], s[92:93]
	s_cbranch_scc1 .LBB0_463
	v_mul_f32_e32 v137, v137, v137
	v_fmac_f32_e32 v137, v136, v136
	v_mul_f32_e32 v136, v139, v139
	v_fmac_f32_e32 v136, v138, v138
	v_mul_f32_e32 v133, v133, v133
	v_add_f32_e32 v136, v137, v136
	v_fmac_f32_e32 v133, v132, v132
	v_add_f32_e32 v132, v133, v136
	v_mul_f32_e32 v133, v135, v135
	v_fmac_f32_e32 v133, v134, v134
	v_and_b32_e32 v134, 64, v1
	v_add_f32_e32 v132, v133, v132
	v_add_u32_e32 v134, 64, v134
	v_mov_b32_e32 v133, v132
	s_nop 1
	v_permlane16_swap_b32_e32 v132, v133
	s_waitcnt lgkmcnt(0)
	v_add_f32_e32 v132, v132, v133
	v_mov_b32_e32 v133, v132
	s_nop 1
	v_permlane32_swap_b32_e32 v132, v133
	s_and_saveexec_b64 s[42:43], s[40:41]
	s_cbranch_execz .LBB0_462
	s_lshl_b32 s55, s49, 4
	v_lshl_add_u32 v134, v167, 2, s55
	s_waitcnt lgkmcnt(0)
	v_add_f32_e32 v132, v132, v133
	global_store_dword v134, v132, s[74:75]

.LBB0_465:
	v_add_u32_e32 v133, s1, v133
	v_lshl_add_u32 v135, v133, 12, v166
	v_mul_lo_u32 v133, v133, 20
	v_or_b32_e32 v134, s13, v133
	s_waitcnt lgkmcnt(0)
	v_pk_fma_f32 v[130:131], v[130:131], v[132:133], v[110:111] op_sel_hi:[1,0,1]
	v_pk_fma_f32 v[128:129], v[128:129], v[132:133], v[108:109] op_sel_hi:[1,0,1]
	v_pk_fma_f32 v[126:127], v[126:127], v[132:133], v[102:103] op_sel_hi:[1,0,1]
	v_pk_fma_f32 v[124:125], v[124:125], v[132:133], v[100:101] op_sel_hi:[1,0,1]
	v_cndmask_b32_e64 v133, 0, 1, s[44:45]
	v_cvt_pk_bf16_f32 v136, v128, v129
	v_cvt_pk_bf16_f32 v137, v130, v131
	v_cvt_pk_bf16_f32 v138, v124, v125
	v_cvt_pk_bf16_f32 v139, v126, v127
	v_cmp_ne_u32_e64 s[42:43], 1, v133
	s_andn2_b64 vcc, exec, s[44:45]
	global_store_dwordx4 v135, v[136:139], s[92:93]
	s_cbranch_vccnz .LBB0_469
	v_mul_f32_e32 v129, v129, v129
	v_fmac_f32_e32 v129, v128, v128
	v_mul_f32_e32 v128, v131, v131
	v_fmac_f32_e32 v128, v130, v130
	v_mul_f32_e32 v125, v125, v125
	v_add_f32_e32 v128, v129, v128
	v_fmac_f32_e32 v125, v124, v124
	v_add_f32_e32 v124, v125, v128
	v_mul_f32_e32 v125, v127, v127
	v_fmac_f32_e32 v125, v126, v126
	v_and_b32_e32 v126, 64, v1
	v_add_f32_e32 v124, v125, v124
	v_add_u32_e32 v126, 64, v126
	v_mov_b32_e32 v125, v124
	s_nop 1
	v_permlane16_swap_b32_e32 v124, v125
	s_waitcnt lgkmcnt(0)
	v_add_f32_e32 v124, v124, v125
	v_mov_b32_e32 v125, v124
	s_nop 1
	v_permlane32_swap_b32_e32 v124, v125
	s_and_saveexec_b64 s[44:45], s[40:41]
	s_cbranch_execz .LBB0_468
	s_lshl_b32 s55, s0, 5
	v_lshl_add_u32 v126, v134, 2, s55
	s_waitcnt lgkmcnt(0)
	v_add_f32_e32 v124, v124, v125
	global_store_dword v126, v124, s[74:75]

.LBB0_469:
	v_mov_b32_e32 v133, v132
	v_mov_b32_e32 v124, v132
	s_waitcnt lgkmcnt(0)
	v_mov_b32_e32 v125, v132
	v_pk_fma_f32 v[122:123], v[122:123], v[124:125], v[96:97]
	v_pk_fma_f32 v[120:121], v[120:121], v[132:133], v[94:95]
	v_pk_fma_f32 v[118:119], v[118:119], v[124:125], v[92:93]
	v_pk_fma_f32 v[116:117], v[116:117], v[132:133], v[90:91]
	v_cndmask_b32_e64 v129, 0, 1, s[62:63]
	v_cvt_pk_bf16_f32 v124, v120, v121
	v_cvt_pk_bf16_f32 v125, v122, v123
	v_cvt_pk_bf16_f32 v126, v116, v117
	v_cvt_pk_bf16_f32 v127, v118, v119
	v_or_b32_e32 v128, 0x100, v135
	v_cmp_ne_u32_e64 s[44:45], 1, v129
	s_andn2_b64 vcc, exec, s[62:63]
	global_store_dwordx4 v128, v[124:127], s[92:93]
	s_cbranch_vccnz .LBB0_473
	v_mul_f32_e32 v121, v121, v121
	v_fmac_f32_e32 v121, v120, v120
	v_mul_f32_e32 v120, v123, v123
	v_fmac_f32_e32 v120, v122, v122
	v_mul_f32_e32 v117, v117, v117
	v_add_f32_e32 v120, v121, v120
	v_fmac_f32_e32 v117, v116, v116
	v_add_f32_e32 v116, v117, v120
	v_mul_f32_e32 v117, v119, v119
	v_fmac_f32_e32 v117, v118, v118
	v_and_b32_e32 v118, 64, v1
	v_add_f32_e32 v116, v117, v116
	v_add_u32_e32 v118, 64, v118
	v_mov_b32_e32 v117, v116
	s_nop 1
	v_permlane16_swap_b32_e32 v116, v117
	s_waitcnt lgkmcnt(0)
	v_add_f32_e32 v116, v116, v117
	v_mov_b32_e32 v117, v116
	s_nop 1
	v_permlane32_swap_b32_e32 v116, v117
	s_and_saveexec_b64 s[62:63], s[40:41]
	s_cbranch_execz .LBB0_472
	s_lshl_b32 s55, s49, 4
	v_lshl_add_u32 v118, v134, 2, s55
	s_waitcnt lgkmcnt(0)
	v_add_f32_e32 v116, v116, v117
	global_store_dword v118, v116, s[74:75]

.LBB0_475:
	v_add_u32_e32 v117, s1, v117
	v_lshl_add_u32 v119, v117, 12, v166
	v_mul_lo_u32 v117, v117, 20
	s_waitcnt lgkmcnt(0)
	v_pk_fma_f32 v[114:115], v[114:115], v[116:117], v[110:111] op_sel_hi:[1,0,1]
	v_pk_fma_f32 v[112:113], v[112:113], v[116:117], v[108:109] op_sel_hi:[1,0,1]
	v_pk_fma_f32 v[106:107], v[106:107], v[116:117], v[102:103] op_sel_hi:[1,0,1]
	v_pk_fma_f32 v[104:105], v[104:105], v[116:117], v[100:101] op_sel_hi:[1,0,1]
	v_or_b32_e32 v118, s13, v117
	v_cvt_pk_bf16_f32 v120, v112, v113
	v_cvt_pk_bf16_f32 v121, v114, v115
	v_cvt_pk_bf16_f32 v122, v104, v105
	v_cvt_pk_bf16_f32 v123, v106, v107
	s_and_b64 vcc, exec, s[42:43]
	global_store_dwordx4 v119, v[120:123], s[92:93]
	s_cbranch_vccnz .LBB0_479
	v_mul_f32_e32 v113, v113, v113
	v_fmac_f32_e32 v113, v112, v112
	v_mul_f32_e32 v112, v115, v115
	v_fmac_f32_e32 v112, v114, v114
	v_mul_f32_e32 v105, v105, v105
	v_add_f32_e32 v112, v113, v112
	v_fmac_f32_e32 v105, v104, v104
	v_add_f32_e32 v104, v105, v112
	v_mul_f32_e32 v105, v107, v107
	v_fmac_f32_e32 v105, v106, v106
	v_and_b32_e32 v106, 64, v1
	v_add_f32_e32 v104, v105, v104
	v_add_u32_e32 v106, 64, v106
	v_mov_b32_e32 v105, v104
	s_nop 1
	v_permlane16_swap_b32_e32 v104, v105
	s_waitcnt lgkmcnt(0)
	v_add_f32_e32 v104, v104, v105
	v_mov_b32_e32 v105, v104
	s_nop 1
	v_permlane32_swap_b32_e32 v104, v105
	s_and_saveexec_b64 s[62:63], s[40:41]
	s_cbranch_execz .LBB0_478
	s_lshl_b32 s55, s0, 5
	v_lshl_add_u32 v106, v118, 2, s55
	s_waitcnt lgkmcnt(0)
	v_add_f32_e32 v104, v104, v105
	global_store_dword v106, v104, s[74:75]

.LBB0_479:
	v_mov_b32_e32 v117, v116
	v_mov_b32_e32 v104, v116
	s_waitcnt lgkmcnt(0)
	v_mov_b32_e32 v105, v116
	v_pk_fma_f32 v[88:89], v[88:89], v[104:105], v[96:97]
	v_pk_fma_f32 v[86:87], v[86:87], v[116:117], v[94:95]
	v_pk_fma_f32 v[84:85], v[84:85], v[104:105], v[92:93]
	v_pk_fma_f32 v[82:83], v[82:83], v[116:117], v[90:91]
	v_cvt_pk_bf16_f32 v104, v86, v87
	v_cvt_pk_bf16_f32 v105, v88, v89
	v_cvt_pk_bf16_f32 v106, v82, v83
	v_cvt_pk_bf16_f32 v107, v84, v85
	v_or_b32_e32 v112, 0x100, v119
	s_and_b64 vcc, exec, s[44:45]
	global_store_dwordx4 v112, v[104:107], s[92:93]
	s_cbranch_vccnz .LBB0_483
	v_mul_f32_e32 v87, v87, v87
	v_fmac_f32_e32 v87, v86, v86
	v_mul_f32_e32 v86, v89, v89
	v_fmac_f32_e32 v86, v88, v88
	v_mul_f32_e32 v83, v83, v83
	v_add_f32_e32 v86, v87, v86
	v_fmac_f32_e32 v83, v82, v82
	v_add_f32_e32 v82, v83, v86
	v_mul_f32_e32 v83, v85, v85
	v_fmac_f32_e32 v83, v84, v84
	v_and_b32_e32 v84, 64, v1
	v_add_f32_e32 v82, v83, v82
	v_add_u32_e32 v84, 64, v84
	v_mov_b32_e32 v83, v82
	s_nop 1
	v_permlane16_swap_b32_e32 v82, v83
	s_waitcnt lgkmcnt(0)
	v_add_f32_e32 v82, v82, v83
	v_mov_b32_e32 v83, v82
	s_nop 1
	v_permlane32_swap_b32_e32 v82, v83
	s_and_saveexec_b64 s[62:63], s[40:41]
	s_cbranch_execz .LBB0_482
	s_lshl_b32 s55, s49, 4
	v_lshl_add_u32 v84, v118, 2, s55
	s_waitcnt lgkmcnt(0)
	v_add_f32_e32 v82, v82, v83
	global_store_dword v84, v82, s[74:75]

.LBB0_485:
	v_add_u32_e32 v83, s1, v83
	v_lshl_add_u32 v85, v83, 12, v166
	v_mul_lo_u32 v83, v83, 20
	s_waitcnt lgkmcnt(0)
	v_pk_fma_f32 v[80:81], v[80:81], v[82:83], v[110:111] op_sel_hi:[1,0,1]
	v_pk_fma_f32 v[78:79], v[78:79], v[82:83], v[108:109] op_sel_hi:[1,0,1]
	v_pk_fma_f32 v[76:77], v[76:77], v[82:83], v[102:103] op_sel_hi:[1,0,1]
	v_pk_fma_f32 v[74:75], v[74:75], v[82:83], v[100:101] op_sel_hi:[1,0,1]
	v_or_b32_e32 v84, s13, v83
	v_cvt_pk_bf16_f32 v86, v78, v79
	v_cvt_pk_bf16_f32 v87, v80, v81
	v_cvt_pk_bf16_f32 v88, v74, v75
	v_cvt_pk_bf16_f32 v89, v76, v77
	s_and_b64 vcc, exec, s[42:43]
	global_store_dwordx4 v85, v[86:89], s[92:93]
	s_cbranch_vccnz .LBB0_489
	v_mul_f32_e32 v79, v79, v79
	v_fmac_f32_e32 v79, v78, v78
	v_mul_f32_e32 v78, v81, v81
	v_fmac_f32_e32 v78, v80, v80
	v_mul_f32_e32 v75, v75, v75
	v_add_f32_e32 v78, v79, v78
	v_fmac_f32_e32 v75, v74, v74
	v_add_f32_e32 v74, v75, v78
	v_mul_f32_e32 v75, v77, v77
	v_fmac_f32_e32 v75, v76, v76
	v_and_b32_e32 v76, 64, v1
	v_add_f32_e32 v74, v75, v74
	v_add_u32_e32 v76, 64, v76
	v_mov_b32_e32 v75, v74
	s_nop 1
	v_permlane16_swap_b32_e32 v74, v75
	s_waitcnt lgkmcnt(0)
	v_add_f32_e32 v74, v74, v75
	v_mov_b32_e32 v75, v74
	s_nop 1
	v_permlane32_swap_b32_e32 v74, v75
	s_and_saveexec_b64 s[62:63], s[40:41]
	s_cbranch_execz .LBB0_488
	s_lshl_b32 s55, s0, 5
	v_lshl_add_u32 v76, v84, 2, s55
	s_waitcnt lgkmcnt(0)
	v_add_f32_e32 v74, v74, v75
	global_store_dword v76, v74, s[74:75]

.LBB0_489:
	v_mov_b32_e32 v83, v82
	v_mov_b32_e32 v74, v82
	s_waitcnt lgkmcnt(0)
	v_mov_b32_e32 v75, v82
	v_pk_fma_f32 v[72:73], v[72:73], v[74:75], v[96:97]
	v_pk_fma_f32 v[70:71], v[70:71], v[82:83], v[94:95]
	v_pk_fma_f32 v[68:69], v[68:69], v[74:75], v[92:93]
	v_pk_fma_f32 v[66:67], v[66:67], v[82:83], v[90:91]
	v_cvt_pk_bf16_f32 v74, v70, v71
	v_cvt_pk_bf16_f32 v75, v72, v73
	v_cvt_pk_bf16_f32 v76, v66, v67
	v_cvt_pk_bf16_f32 v77, v68, v69
	v_or_b32_e32 v78, 0x100, v85
	s_and_b64 vcc, exec, s[44:45]
	global_store_dwordx4 v78, v[74:77], s[92:93]
	s_cbranch_vccnz .LBB0_493
	v_mul_f32_e32 v71, v71, v71
	v_fmac_f32_e32 v71, v70, v70
	v_mul_f32_e32 v70, v73, v73
	v_fmac_f32_e32 v70, v72, v72
	v_mul_f32_e32 v67, v67, v67
	v_add_f32_e32 v70, v71, v70
	v_fmac_f32_e32 v67, v66, v66
	v_add_f32_e32 v66, v67, v70
	v_mul_f32_e32 v67, v69, v69
	v_fmac_f32_e32 v67, v68, v68
	v_and_b32_e32 v68, 64, v1
	v_add_f32_e32 v66, v67, v66
	v_add_u32_e32 v68, 64, v68
	v_mov_b32_e32 v67, v66
	s_nop 1
	v_permlane16_swap_b32_e32 v66, v67
	s_waitcnt lgkmcnt(0)
	v_add_f32_e32 v66, v66, v67
	v_mov_b32_e32 v67, v66
	s_nop 1
	v_permlane32_swap_b32_e32 v66, v67
	s_and_saveexec_b64 s[62:63], s[40:41]
	s_cbranch_execz .LBB0_492
	s_lshl_b32 s55, s49, 4
	v_lshl_add_u32 v68, v84, 2, s55
	s_waitcnt lgkmcnt(0)
	v_add_f32_e32 v66, v66, v67
	global_store_dword v68, v66, s[74:75]

.LBB0_495:
	v_add_u32_e32 v67, s1, v67
	v_lshl_add_u32 v69, v67, 12, v166
	v_mul_lo_u32 v67, v67, 20
	s_waitcnt lgkmcnt(0)
	v_pk_fma_f32 v[64:65], v[64:65], v[66:67], v[110:111] op_sel_hi:[1,0,1]
	v_pk_fma_f32 v[62:63], v[62:63], v[66:67], v[108:109] op_sel_hi:[1,0,1]
	v_pk_fma_f32 v[60:61], v[60:61], v[66:67], v[102:103] op_sel_hi:[1,0,1]
	v_pk_fma_f32 v[58:59], v[58:59], v[66:67], v[100:101] op_sel_hi:[1,0,1]
	v_or_b32_e32 v68, s13, v67
	v_cvt_pk_bf16_f32 v70, v62, v63
	v_cvt_pk_bf16_f32 v71, v64, v65
	v_cvt_pk_bf16_f32 v72, v58, v59
	v_cvt_pk_bf16_f32 v73, v60, v61
	s_and_b64 vcc, exec, s[42:43]
	global_store_dwordx4 v69, v[70:73], s[92:93]
	s_cbranch_vccnz .LBB0_499
	v_mul_f32_e32 v63, v63, v63
	v_fmac_f32_e32 v63, v62, v62
	v_mul_f32_e32 v62, v65, v65
	v_fmac_f32_e32 v62, v64, v64
	v_mul_f32_e32 v59, v59, v59
	v_add_f32_e32 v62, v63, v62
	v_fmac_f32_e32 v59, v58, v58
	v_add_f32_e32 v58, v59, v62
	v_mul_f32_e32 v59, v61, v61
	v_fmac_f32_e32 v59, v60, v60
	v_and_b32_e32 v60, 64, v1
	v_add_f32_e32 v58, v59, v58
	v_add_u32_e32 v60, 64, v60
	v_mov_b32_e32 v59, v58
	s_nop 1
	v_permlane16_swap_b32_e32 v58, v59
	s_waitcnt lgkmcnt(0)
	v_add_f32_e32 v58, v58, v59
	v_mov_b32_e32 v59, v58
	s_nop 1
	v_permlane32_swap_b32_e32 v58, v59
	s_and_saveexec_b64 s[62:63], s[40:41]
	s_cbranch_execz .LBB0_498
	s_lshl_b32 s55, s0, 5
	v_lshl_add_u32 v60, v68, 2, s55
	s_waitcnt lgkmcnt(0)
	v_add_f32_e32 v58, v58, v59
	global_store_dword v60, v58, s[74:75]

.LBB0_499:
	v_mov_b32_e32 v67, v66
	v_mov_b32_e32 v58, v66
	s_waitcnt lgkmcnt(0)
	v_mov_b32_e32 v59, v66
	v_pk_fma_f32 v[56:57], v[56:57], v[58:59], v[96:97]
	v_pk_fma_f32 v[54:55], v[54:55], v[66:67], v[94:95]
	v_pk_fma_f32 v[52:53], v[52:53], v[58:59], v[92:93]
	v_pk_fma_f32 v[50:51], v[50:51], v[66:67], v[90:91]
	v_cvt_pk_bf16_f32 v58, v54, v55
	v_cvt_pk_bf16_f32 v59, v56, v57
	v_cvt_pk_bf16_f32 v60, v50, v51
	v_cvt_pk_bf16_f32 v61, v52, v53
	v_or_b32_e32 v62, 0x100, v69
	s_and_b64 vcc, exec, s[44:45]
	global_store_dwordx4 v62, v[58:61], s[92:93]
	s_cbranch_vccnz .LBB0_503
	v_mul_f32_e32 v55, v55, v55
	v_fmac_f32_e32 v55, v54, v54
	v_mul_f32_e32 v54, v57, v57
	v_fmac_f32_e32 v54, v56, v56
	v_mul_f32_e32 v51, v51, v51
	v_add_f32_e32 v54, v55, v54
	v_fmac_f32_e32 v51, v50, v50
	v_add_f32_e32 v50, v51, v54
	v_mul_f32_e32 v51, v53, v53
	v_fmac_f32_e32 v51, v52, v52
	v_and_b32_e32 v52, 64, v1
	v_add_f32_e32 v50, v51, v50
	v_add_u32_e32 v52, 64, v52
	v_mov_b32_e32 v51, v50
	s_nop 1
	v_permlane16_swap_b32_e32 v50, v51
	s_waitcnt lgkmcnt(0)
	v_add_f32_e32 v50, v50, v51
	v_mov_b32_e32 v51, v50
	s_nop 1
	v_permlane32_swap_b32_e32 v50, v51
	s_and_saveexec_b64 s[62:63], s[40:41]
	s_cbranch_execz .LBB0_502
	s_lshl_b32 s55, s49, 4
	v_lshl_add_u32 v52, v68, 2, s55
	s_waitcnt lgkmcnt(0)
	v_add_f32_e32 v50, v50, v51
	global_store_dword v52, v50, s[74:75]

.LBB0_505:
	v_add_u32_e32 v51, s1, v51
	v_lshl_add_u32 v53, v51, 12, v166
	v_mul_lo_u32 v51, v51, 20
	s_waitcnt lgkmcnt(0)
	v_pk_fma_f32 v[48:49], v[48:49], v[50:51], v[110:111] op_sel_hi:[1,0,1]
	v_pk_fma_f32 v[46:47], v[46:47], v[50:51], v[108:109] op_sel_hi:[1,0,1]
	v_pk_fma_f32 v[44:45], v[44:45], v[50:51], v[102:103] op_sel_hi:[1,0,1]
	v_pk_fma_f32 v[42:43], v[42:43], v[50:51], v[100:101] op_sel_hi:[1,0,1]
	v_or_b32_e32 v52, s13, v51
	v_cvt_pk_bf16_f32 v54, v46, v47
	v_cvt_pk_bf16_f32 v55, v48, v49
	v_cvt_pk_bf16_f32 v56, v42, v43
	v_cvt_pk_bf16_f32 v57, v44, v45
	s_and_b64 vcc, exec, s[42:43]
	global_store_dwordx4 v53, v[54:57], s[92:93]
	s_cbranch_vccnz .LBB0_509
	v_mul_f32_e32 v47, v47, v47
	v_fmac_f32_e32 v47, v46, v46
	v_mul_f32_e32 v46, v49, v49
	v_fmac_f32_e32 v46, v48, v48
	v_mul_f32_e32 v43, v43, v43
	v_add_f32_e32 v46, v47, v46
	v_fmac_f32_e32 v43, v42, v42
	v_add_f32_e32 v42, v43, v46
	v_mul_f32_e32 v43, v45, v45
	v_fmac_f32_e32 v43, v44, v44
	v_and_b32_e32 v44, 64, v1
	v_add_f32_e32 v42, v43, v42
	v_add_u32_e32 v44, 64, v44
	v_mov_b32_e32 v43, v42
	s_nop 1
	v_permlane16_swap_b32_e32 v42, v43
	s_waitcnt lgkmcnt(0)
	v_add_f32_e32 v42, v42, v43
	v_mov_b32_e32 v43, v42
	s_nop 1
	v_permlane32_swap_b32_e32 v42, v43
	s_and_saveexec_b64 s[62:63], s[40:41]
	s_cbranch_execz .LBB0_508
	s_lshl_b32 s55, s0, 5
	v_lshl_add_u32 v44, v52, 2, s55
	s_waitcnt lgkmcnt(0)
	v_add_f32_e32 v42, v42, v43
	global_store_dword v44, v42, s[74:75]

.LBB0_509:
	v_mov_b32_e32 v51, v50
	v_mov_b32_e32 v42, v50
	s_waitcnt lgkmcnt(0)
	v_mov_b32_e32 v43, v50
	v_pk_fma_f32 v[40:41], v[40:41], v[42:43], v[96:97]
	v_pk_fma_f32 v[38:39], v[38:39], v[50:51], v[94:95]
	v_pk_fma_f32 v[36:37], v[36:37], v[42:43], v[92:93]
	v_pk_fma_f32 v[34:35], v[34:35], v[50:51], v[90:91]
	v_cvt_pk_bf16_f32 v42, v38, v39
	v_cvt_pk_bf16_f32 v43, v40, v41
	v_cvt_pk_bf16_f32 v44, v34, v35
	v_cvt_pk_bf16_f32 v45, v36, v37
	v_or_b32_e32 v46, 0x100, v53
	s_and_b64 vcc, exec, s[44:45]
	global_store_dwordx4 v46, v[42:45], s[92:93]
	s_cbranch_vccnz .LBB0_513
	v_mul_f32_e32 v39, v39, v39
	v_fmac_f32_e32 v39, v38, v38
	v_mul_f32_e32 v38, v41, v41
	v_fmac_f32_e32 v38, v40, v40
	v_mul_f32_e32 v35, v35, v35
	v_add_f32_e32 v38, v39, v38
	v_fmac_f32_e32 v35, v34, v34
	v_add_f32_e32 v34, v35, v38
	v_mul_f32_e32 v35, v37, v37
	v_fmac_f32_e32 v35, v36, v36
	v_and_b32_e32 v36, 64, v1
	v_add_f32_e32 v34, v35, v34
	v_add_u32_e32 v36, 64, v36
	v_mov_b32_e32 v35, v34
	s_nop 1
	v_permlane16_swap_b32_e32 v34, v35
	s_waitcnt lgkmcnt(0)
	v_add_f32_e32 v34, v34, v35
	v_mov_b32_e32 v35, v34
	s_nop 1
	v_permlane32_swap_b32_e32 v34, v35
	s_and_saveexec_b64 s[62:63], s[40:41]
	s_cbranch_execz .LBB0_512
	s_lshl_b32 s55, s49, 4
	v_lshl_add_u32 v36, v52, 2, s55
	s_waitcnt lgkmcnt(0)
	v_add_f32_e32 v34, v34, v35
	global_store_dword v36, v34, s[74:75]

.LBB0_515:
	v_add_u32_e32 v35, s1, v35
	v_lshl_add_u32 v37, v35, 12, v166
	v_mul_lo_u32 v35, v35, 20
	s_waitcnt lgkmcnt(0)
	v_pk_fma_f32 v[32:33], v[32:33], v[34:35], v[110:111] op_sel_hi:[1,0,1]
	v_pk_fma_f32 v[30:31], v[30:31], v[34:35], v[108:109] op_sel_hi:[1,0,1]
	v_pk_fma_f32 v[28:29], v[28:29], v[34:35], v[102:103] op_sel_hi:[1,0,1]
	v_pk_fma_f32 v[26:27], v[26:27], v[34:35], v[100:101] op_sel_hi:[1,0,1]
	v_or_b32_e32 v36, s13, v35
	v_cvt_pk_bf16_f32 v38, v30, v31
	v_cvt_pk_bf16_f32 v39, v32, v33
	v_cvt_pk_bf16_f32 v40, v26, v27
	v_cvt_pk_bf16_f32 v41, v28, v29
	s_and_b64 vcc, exec, s[42:43]
	global_store_dwordx4 v37, v[38:41], s[92:93]
	s_cbranch_vccnz .LBB0_519
	v_mul_f32_e32 v31, v31, v31
	v_fmac_f32_e32 v31, v30, v30
	v_mul_f32_e32 v30, v33, v33
	v_fmac_f32_e32 v30, v32, v32
	v_mul_f32_e32 v27, v27, v27
	v_add_f32_e32 v30, v31, v30
	v_fmac_f32_e32 v27, v26, v26
	v_add_f32_e32 v26, v27, v30
	v_mul_f32_e32 v27, v29, v29
	v_fmac_f32_e32 v27, v28, v28
	v_and_b32_e32 v28, 64, v1
	v_add_f32_e32 v26, v27, v26
	v_add_u32_e32 v28, 64, v28
	v_mov_b32_e32 v27, v26
	s_nop 1
	v_permlane16_swap_b32_e32 v26, v27
	s_waitcnt lgkmcnt(0)
	v_add_f32_e32 v26, v26, v27
	v_mov_b32_e32 v27, v26
	s_nop 1
	v_permlane32_swap_b32_e32 v26, v27
	s_and_saveexec_b64 s[62:63], s[40:41]
	s_cbranch_execz .LBB0_518
	s_lshl_b32 s55, s0, 5
	v_lshl_add_u32 v28, v36, 2, s55
	s_waitcnt lgkmcnt(0)
	v_add_f32_e32 v26, v26, v27
	global_store_dword v28, v26, s[74:75]

.LBB0_519:
	v_mov_b32_e32 v35, v34
	v_mov_b32_e32 v26, v34
	s_waitcnt lgkmcnt(0)
	v_mov_b32_e32 v27, v34
	v_pk_fma_f32 v[24:25], v[24:25], v[26:27], v[96:97]
	v_pk_fma_f32 v[22:23], v[22:23], v[34:35], v[94:95]
	v_pk_fma_f32 v[20:21], v[20:21], v[26:27], v[92:93]
	v_pk_fma_f32 v[18:19], v[18:19], v[34:35], v[90:91]
	v_cvt_pk_bf16_f32 v26, v22, v23
	v_cvt_pk_bf16_f32 v27, v24, v25
	v_cvt_pk_bf16_f32 v28, v18, v19
	v_cvt_pk_bf16_f32 v29, v20, v21
	v_or_b32_e32 v30, 0x100, v37
	s_and_b64 vcc, exec, s[44:45]
	global_store_dwordx4 v30, v[26:29], s[92:93]
	s_cbranch_vccnz .LBB0_523
	v_mul_f32_e32 v23, v23, v23
	v_fmac_f32_e32 v23, v22, v22
	v_mul_f32_e32 v22, v25, v25
	v_fmac_f32_e32 v22, v24, v24
	v_mul_f32_e32 v19, v19, v19
	v_add_f32_e32 v22, v23, v22
	v_fmac_f32_e32 v19, v18, v18
	v_add_f32_e32 v18, v19, v22
	v_mul_f32_e32 v19, v21, v21
	v_fmac_f32_e32 v19, v20, v20
	v_and_b32_e32 v20, 64, v1
	v_add_f32_e32 v18, v19, v18
	v_add_u32_e32 v20, 64, v20
	v_mov_b32_e32 v19, v18
	s_nop 1
	v_permlane16_swap_b32_e32 v18, v19
	s_waitcnt lgkmcnt(0)
	v_add_f32_e32 v18, v18, v19
	v_mov_b32_e32 v19, v18
	s_nop 1
	v_permlane32_swap_b32_e32 v18, v19
	s_and_saveexec_b64 s[62:63], s[40:41]
	s_cbranch_execz .LBB0_522
	s_lshl_b32 s55, s49, 4
	v_lshl_add_u32 v20, v36, 2, s55
	s_waitcnt lgkmcnt(0)
	v_add_f32_e32 v18, v18, v19
	global_store_dword v20, v18, s[74:75]

.LBB0_525:
	v_add_u32_e32 v19, s1, v19
	v_lshl_add_u32 v21, v19, 12, v166
	v_mul_lo_u32 v19, v19, 20
	s_waitcnt lgkmcnt(0)
	v_pk_fma_f32 v[16:17], v[16:17], v[18:19], v[110:111] op_sel_hi:[1,0,1]
	v_pk_fma_f32 v[14:15], v[14:15], v[18:19], v[108:109] op_sel_hi:[1,0,1]
	v_pk_fma_f32 v[12:13], v[12:13], v[18:19], v[102:103] op_sel_hi:[1,0,1]
	v_pk_fma_f32 v[10:11], v[10:11], v[18:19], v[100:101] op_sel_hi:[1,0,1]
	v_or_b32_e32 v20, s13, v19
	v_cvt_pk_bf16_f32 v22, v14, v15
	v_cvt_pk_bf16_f32 v23, v16, v17
	v_cvt_pk_bf16_f32 v24, v10, v11
	v_cvt_pk_bf16_f32 v25, v12, v13
	s_and_b64 vcc, exec, s[42:43]
	global_store_dwordx4 v21, v[22:25], s[92:93]
	s_cbranch_vccnz .LBB0_529
	v_mul_f32_e32 v15, v15, v15
	v_fmac_f32_e32 v15, v14, v14
	v_mul_f32_e32 v14, v17, v17
	v_fmac_f32_e32 v14, v16, v16
	v_mul_f32_e32 v11, v11, v11
	v_add_f32_e32 v14, v15, v14
	v_fmac_f32_e32 v11, v10, v10
	v_add_f32_e32 v10, v11, v14
	v_mul_f32_e32 v11, v13, v13
	v_fmac_f32_e32 v11, v12, v12
	v_and_b32_e32 v12, 64, v1
	v_add_f32_e32 v10, v11, v10
	v_add_u32_e32 v12, 64, v12
	v_mov_b32_e32 v11, v10
	s_nop 1
	v_permlane16_swap_b32_e32 v10, v11
	s_waitcnt lgkmcnt(0)
	v_add_f32_e32 v10, v10, v11
	v_mov_b32_e32 v11, v10
	s_nop 1
	v_permlane32_swap_b32_e32 v10, v11
	s_and_saveexec_b64 s[42:43], s[40:41]
	s_cbranch_execz .LBB0_528
	s_lshl_b32 s0, s0, 5
	v_lshl_add_u32 v12, v20, 2, s0
	s_waitcnt lgkmcnt(0)
	v_add_f32_e32 v10, v10, v11
	global_store_dword v12, v10, s[74:75]

.LBB0_529:
	v_mov_b32_e32 v19, v18
	v_mov_b32_e32 v10, v18
	s_waitcnt lgkmcnt(0)
	v_mov_b32_e32 v11, v18
	v_pk_fma_f32 v[8:9], v[8:9], v[10:11], v[96:97]
	v_pk_fma_f32 v[6:7], v[6:7], v[18:19], v[94:95]
	v_pk_fma_f32 v[4:5], v[4:5], v[10:11], v[92:93]
	v_pk_fma_f32 v[2:3], v[2:3], v[18:19], v[90:91]
	v_cvt_pk_bf16_f32 v10, v6, v7
	v_cvt_pk_bf16_f32 v11, v8, v9
	v_cvt_pk_bf16_f32 v12, v2, v3
	v_cvt_pk_bf16_f32 v13, v4, v5
	v_or_b32_e32 v14, 0x100, v21
	s_and_b64 vcc, exec, s[44:45]
	global_store_dwordx4 v14, v[10:13], s[92:93]
	s_cbranch_vccnz .LBB0_533
	v_mul_f32_e32 v7, v7, v7
	v_fmac_f32_e32 v7, v6, v6
	v_mul_f32_e32 v6, v9, v9
	v_fmac_f32_e32 v6, v8, v8
	v_mul_f32_e32 v3, v3, v3
	v_add_f32_e32 v6, v7, v6
	v_fmac_f32_e32 v3, v2, v2
	v_add_f32_e32 v2, v3, v6
	v_mul_f32_e32 v3, v5, v5
	v_fmac_f32_e32 v3, v4, v4
	v_and_b32_e32 v4, 64, v1
	v_add_f32_e32 v2, v3, v2
	v_add_u32_e32 v4, 64, v4
	v_mov_b32_e32 v3, v2
	s_nop 1
	v_permlane16_swap_b32_e32 v2, v3
	s_waitcnt lgkmcnt(0)
	v_add_f32_e32 v2, v2, v3
	v_mov_b32_e32 v3, v2
	s_nop 1
	v_permlane32_swap_b32_e32 v2, v3
	s_and_saveexec_b64 s[0:1], s[40:41]
	s_cbranch_execz .LBB0_532
	s_lshl_b32 s40, s49, 4
	v_lshl_add_u32 v4, v20, 2, s40
	s_waitcnt lgkmcnt(0)
	v_add_f32_e32 v2, v2, v3
	global_store_dword v4, v2, s[74:75]

.LBB0_1331:
	v_mov_b32_e32 v215, v0
	v_and_b32_e32 v217, 64, v1
	v_bfe_u32 v162, v215, 4, 2
	v_lshl_or_b32 v197, v162, 3, s8
	v_lshlrev_b32_e32 v221, 4, v162
	v_xor_b32_e32 v162, 16, v1
	v_add_u32_e32 v163, 64, v217
	v_cmp_lt_i32_e32 vcc, v162, v163
	v_and_b32_e32 v216, 15, v215
	v_or_b32_e32 v189, s94, v216
	v_cndmask_b32_e32 v162, v1, v162, vcc
	v_lshlrev_b32_e32 v220, 2, v162
	v_xor_b32_e32 v162, 32, v1
	v_cmp_lt_i32_e32 vcc, v162, v163
	v_lshl_add_u32 v82, v197, 2, 0
	v_add_u32_e32 v218, 0x22000, v82
	v_cndmask_b32_e32 v162, v1, v162, vcc
	v_lshlrev_b32_e32 v219, 2, v162
	v_lshlrev_b32_e32 v162, 6, v189
	v_add3_u32 v162, s16, v162, v221
	ds_read_b128 v[94:97], v218
	ds_read_b128 v[90:93], v218 offset:16
	ds_read_b128 v[86:89], v218 offset:512
	ds_read_b128 v[82:85], v218 offset:528
	ds_read_b128 v[162:165], v162
	v_add_u32_e32 v192, 0x90, v189
	v_add_u32_e32 v194, 0xa0, v189
	v_add_u32_e32 v196, 0xb0, v189
	s_max_i32 s1, s40, 0
	s_waitcnt lgkmcnt(0)
	v_mov_b32_e32 v166, v163
	v_mov_b32_e32 v167, v164
	v_mov_b32_e32 v163, v165
	v_pk_add_f32 v[162:163], v[166:167], v[162:163]
	s_and_b32 s1, s1, 0x7ffff800
	v_add_f32_e32 v162, v162, v163
	v_mov_b32_e32 v163, v162
	s_nop 1
	v_permlane16_swap_b32_e32 v162, v163
	s_addk_i32 s1, 0x800
	s_cmpk_lt_i32 s40, 0x4000
	s_cselect_b32 s1, s1, 2.0
	v_add_u32_e32 v198, s40, v189
	s_waitcnt lgkmcnt(0)
	v_add_f32_e32 v162, v162, v163
	v_mov_b32_e32 v163, v162
	s_nop 1
	v_permlane32_swap_b32_e32 v162, v163
	v_add_u32_e32 v191, s40, v192
	v_add_u32_e32 v193, s40, v194
	v_add_u32_e32 v195, s40, v196
	s_waitcnt lgkmcnt(0)
	v_add_f32_e32 v162, v162, v163
	v_fmamk_f32 v162, v162, 0x3a800000, v212
	v_rsq_f32_e32 v164, v162
	s_nop 0
	v_pk_fma_f32 v[162:163], v[136:137], v[164:165], v[86:87] op_sel_hi:[1,0,1]
	v_or_b32_e32 v136, 16, v189
	v_add_u32_e32 v199, s40, v136
	v_lshlrev_b32_e32 v136, 6, v136
	v_add3_u32 v136, s16, v136, v221
	ds_read_b128 v[168:171], v136
	v_pk_fma_f32 v[166:167], v[144:145], v[164:165], v[94:95] op_sel_hi:[1,0,1]
	v_pk_fma_f32 v[146:147], v[146:147], v[164:165], v[96:97] op_sel_hi:[1,0,1]
	v_pk_fma_f32 v[142:143], v[142:143], v[164:165], v[92:93] op_sel_hi:[1,0,1]
	v_pk_fma_f32 v[140:141], v[140:141], v[164:165], v[90:91] op_sel_hi:[1,0,1]
	s_waitcnt lgkmcnt(0)
	v_mov_b32_e32 v136, v169
	v_mov_b32_e32 v137, v170
	v_mov_b32_e32 v169, v171
	v_pk_add_f32 v[136:137], v[136:137], v[168:169]
	v_pk_fma_f32 v[138:139], v[138:139], v[164:165], v[88:89] op_sel_hi:[1,0,1]
	v_add_f32_e32 v136, v136, v137
	v_mov_b32_e32 v137, v136
	s_nop 1
	v_permlane16_swap_b32_e32 v136, v137
	v_pk_fma_f32 v[134:135], v[134:135], v[164:165], v[84:85] op_sel_hi:[1,0,1]
	v_pk_fma_f32 v[132:133], v[132:133], v[164:165], v[82:83] op_sel_hi:[1,0,1]
	s_waitcnt lgkmcnt(0)
	v_add_f32_e32 v136, v136, v137
	v_mov_b32_e32 v137, v136
	s_nop 1
	v_permlane32_swap_b32_e32 v136, v137
	s_waitcnt lgkmcnt(0)
	v_add_f32_e32 v136, v136, v137
	v_fmamk_f32 v136, v136, 0x3a800000, v212
	v_rsq_f32_e32 v144, v136
	s_nop 0
	v_pk_fma_f32 v[172:173], v[120:121], v[144:145], v[86:87] op_sel_hi:[1,0,1]
	v_or_b32_e32 v120, 32, v189
	v_add_u32_e32 v213, s40, v120
	v_lshlrev_b32_e32 v120, 6, v120
	v_add3_u32 v120, s16, v120, v221
	v_pk_fma_f32 v[136:137], v[122:123], v[144:145], v[88:89] op_sel_hi:[1,0,1]
	ds_read_b128 v[120:123], v120
	v_pk_fma_f32 v[174:175], v[128:129], v[144:145], v[94:95] op_sel_hi:[1,0,1]
	v_pk_fma_f32 v[164:165], v[130:131], v[144:145], v[96:97] op_sel_hi:[1,0,1]
	v_pk_fma_f32 v[126:127], v[126:127], v[144:145], v[92:93] op_sel_hi:[1,0,1]
	v_pk_fma_f32 v[124:125], v[124:125], v[144:145], v[90:91] op_sel_hi:[1,0,1]
	s_waitcnt lgkmcnt(0)
	v_mov_b32_e32 v128, v121
	v_mov_b32_e32 v129, v122
	v_mov_b32_e32 v121, v123
	v_pk_add_f32 v[120:121], v[128:129], v[120:121]
	v_pk_fma_f32 v[118:119], v[118:119], v[144:145], v[84:85] op_sel_hi:[1,0,1]
	v_add_f32_e32 v120, v120, v121
	v_mov_b32_e32 v121, v120
	s_nop 1
	v_permlane16_swap_b32_e32 v120, v121
	v_pk_fma_f32 v[116:117], v[116:117], v[144:145], v[82:83] op_sel_hi:[1,0,1]
	s_waitcnt lgkmcnt(0)
	v_add_f32_e32 v120, v120, v121
	v_mov_b32_e32 v121, v120
	s_nop 1
	v_permlane32_swap_b32_e32 v120, v121
	s_waitcnt lgkmcnt(0)
	v_add_f32_e32 v120, v120, v121
	v_fmamk_f32 v120, v120, 0x3a800000, v212
	v_rsq_f32_e32 v120, v120
	s_nop 0
	v_pk_fma_f32 v[144:145], v[106:107], v[120:121], v[88:89] op_sel_hi:[1,0,1]
	v_pk_fma_f32 v[106:107], v[100:101], v[120:121], v[82:83] op_sel_hi:[1,0,1]
	v_or_b32_e32 v100, 48, v189
	v_add_u32_e32 v214, s40, v100
	v_lshlrev_b32_e32 v100, 6, v100
	v_add3_u32 v100, s16, v100, v221
	v_pk_fma_f32 v[168:169], v[114:115], v[120:121], v[96:97] op_sel_hi:[1,0,1]
	v_pk_fma_f32 v[178:179], v[112:113], v[120:121], v[94:95] op_sel_hi:[1,0,1]
	ds_read_b128 v[112:115], v100
	v_pk_fma_f32 v[110:111], v[110:111], v[120:121], v[92:93] op_sel_hi:[1,0,1]
	v_pk_fma_f32 v[108:109], v[108:109], v[120:121], v[90:91] op_sel_hi:[1,0,1]
	v_pk_fma_f32 v[176:177], v[104:105], v[120:121], v[86:87] op_sel_hi:[1,0,1]
	v_pk_fma_f32 v[102:103], v[102:103], v[120:121], v[84:85] op_sel_hi:[1,0,1]
	s_waitcnt lgkmcnt(0)
	v_mov_b32_e32 v100, v113
	v_mov_b32_e32 v101, v114
	v_mov_b32_e32 v113, v115
	v_pk_add_f32 v[100:101], v[100:101], v[112:113]
	s_nop 0
	v_add_f32_e32 v100, v100, v101
	v_mov_b32_e32 v101, v100
	s_nop 1
	v_permlane16_swap_b32_e32 v100, v101
	s_waitcnt lgkmcnt(0)
	v_add_f32_e32 v100, v100, v101
	v_mov_b32_e32 v101, v100
	s_nop 1
	v_permlane32_swap_b32_e32 v100, v101
	s_waitcnt lgkmcnt(0)
	v_add_f32_e32 v100, v100, v101
	v_fmamk_f32 v100, v100, 0x3a800000, v212
	v_rsq_f32_e32 v100, v100
	s_nop 0
	v_pk_fma_f32 v[128:129], v[66:67], v[100:101], v[82:83] op_sel_hi:[1,0,1]
	v_add_u32_e32 v66, 0x80, v189
	v_add_u32_e32 v190, s40, v66
	v_lshlrev_b32_e32 v66, 6, v66
	v_add3_u32 v66, s16, v66, v221
	v_pk_fma_f32 v[180:181], v[80:81], v[100:101], v[96:97] op_sel_hi:[1,0,1]
	v_pk_fma_f32 v[80:81], v[68:69], v[100:101], v[84:85] op_sel_hi:[1,0,1]
	ds_read_b128 v[66:69], v66
	v_pk_fma_f32 v[182:183], v[70:71], v[100:101], v[86:87] op_sel_hi:[1,0,1]
	v_pk_fma_f32 v[130:131], v[74:75], v[100:101], v[90:91] op_sel_hi:[1,0,1]
	v_pk_fma_f32 v[170:171], v[72:73], v[100:101], v[88:89] op_sel_hi:[1,0,1]
	v_pk_fma_f32 v[122:123], v[76:77], v[100:101], v[92:93] op_sel_hi:[1,0,1]
	s_waitcnt lgkmcnt(0)
	v_mov_b32_e32 v70, v67
	v_mov_b32_e32 v71, v68
	v_mov_b32_e32 v67, v69
	v_pk_add_f32 v[66:67], v[70:71], v[66:67]
	v_pk_fma_f32 v[184:185], v[78:79], v[100:101], v[94:95] op_sel_hi:[1,0,1]
	v_add_f32_e32 v66, v66, v67
	v_mov_b32_e32 v67, v66
	s_nop 1
	v_permlane16_swap_b32_e32 v66, v67
	s_addk_i32 s40, 0xff
	s_cmp_lt_i32 s40, s1
	s_waitcnt lgkmcnt(0)
	v_add_f32_e32 v66, v66, v67
	v_mov_b32_e32 v67, v66
	s_nop 1
	v_permlane32_swap_b32_e32 v66, v67
	s_waitcnt lgkmcnt(0)
	v_add_f32_e32 v66, v66, v67
	v_fmamk_f32 v66, v66, 0x3a800000, v212
	v_rsq_f32_e32 v68, v66
	s_nop 0
	v_pk_fma_f32 v[66:67], v[54:55], v[68:69], v[86:87] op_sel_hi:[1,0,1]
	v_lshlrev_b32_e32 v54, 6, v192
	v_add3_u32 v54, s16, v54, v221
	ds_read_b128 v[72:75], v54
	v_pk_fma_f32 v[70:71], v[62:63], v[68:69], v[94:95] op_sel_hi:[1,0,1]
	v_pk_fma_f32 v[64:65], v[64:65], v[68:69], v[96:97] op_sel_hi:[1,0,1]
	v_pk_fma_f32 v[60:61], v[60:61], v[68:69], v[92:93] op_sel_hi:[1,0,1]
	v_pk_fma_f32 v[58:59], v[58:59], v[68:69], v[90:91] op_sel_hi:[1,0,1]
	s_waitcnt lgkmcnt(0)
	v_mov_b32_e32 v54, v73
	v_mov_b32_e32 v55, v74
	v_mov_b32_e32 v73, v75
	v_pk_add_f32 v[54:55], v[54:55], v[72:73]
	v_pk_fma_f32 v[56:57], v[56:57], v[68:69], v[88:89] op_sel_hi:[1,0,1]
	v_add_f32_e32 v54, v54, v55
	v_mov_b32_e32 v55, v54
	s_nop 1
	v_permlane16_swap_b32_e32 v54, v55
	v_pk_fma_f32 v[52:53], v[52:53], v[68:69], v[84:85] op_sel_hi:[1,0,1]
	v_pk_fma_f32 v[50:51], v[50:51], v[68:69], v[82:83] op_sel_hi:[1,0,1]
	s_waitcnt lgkmcnt(0)
	v_add_f32_e32 v54, v54, v55
	v_mov_b32_e32 v55, v54
	s_nop 1
	v_permlane32_swap_b32_e32 v54, v55
	s_waitcnt lgkmcnt(0)
	v_add_f32_e32 v54, v54, v55
	v_fmamk_f32 v54, v54, 0x3a800000, v212
	v_rsq_f32_e32 v62, v54
	s_nop 0
	v_pk_fma_f32 v[76:77], v[38:39], v[62:63], v[86:87] op_sel_hi:[1,0,1]
	v_lshlrev_b32_e32 v38, 6, v194
	v_add3_u32 v38, s16, v38, v221
	v_pk_fma_f32 v[54:55], v[40:41], v[62:63], v[88:89] op_sel_hi:[1,0,1]
	ds_read_b128 v[38:41], v38
	v_pk_fma_f32 v[78:79], v[46:47], v[62:63], v[94:95] op_sel_hi:[1,0,1]
	v_pk_fma_f32 v[68:69], v[48:49], v[62:63], v[96:97] op_sel_hi:[1,0,1]
	v_pk_fma_f32 v[44:45], v[44:45], v[62:63], v[92:93] op_sel_hi:[1,0,1]
	v_pk_fma_f32 v[42:43], v[42:43], v[62:63], v[90:91] op_sel_hi:[1,0,1]
	s_waitcnt lgkmcnt(0)
	v_mov_b32_e32 v46, v39
	v_mov_b32_e32 v47, v40
	v_mov_b32_e32 v39, v41
	v_pk_add_f32 v[38:39], v[46:47], v[38:39]
	v_pk_fma_f32 v[36:37], v[36:37], v[62:63], v[84:85] op_sel_hi:[1,0,1]
	v_add_f32_e32 v38, v38, v39
	v_mov_b32_e32 v39, v38
	s_nop 1
	v_permlane16_swap_b32_e32 v38, v39
	v_pk_fma_f32 v[34:35], v[34:35], v[62:63], v[82:83] op_sel_hi:[1,0,1]
	s_waitcnt lgkmcnt(0)
	v_add_f32_e32 v38, v38, v39
	v_mov_b32_e32 v39, v38
	s_nop 1
	v_permlane32_swap_b32_e32 v38, v39
	s_waitcnt lgkmcnt(0)
	v_add_f32_e32 v38, v38, v39
	v_fmamk_f32 v38, v38, 0x3a800000, v212
	v_rsq_f32_e32 v40, v38
	s_nop 0
	v_pk_fma_f32 v[72:73], v[32:33], v[40:41], v[96:97] op_sel_hi:[1,0,1]
	v_pk_fma_f32 v[32:33], v[18:19], v[40:41], v[82:83] op_sel_hi:[1,0,1]
	v_lshlrev_b32_e32 v18, 6, v196
	v_add3_u32 v18, s16, v18, v221
	v_pk_fma_f32 v[38:39], v[26:27], v[40:41], v[90:91] op_sel_hi:[1,0,1]
	v_pk_fma_f32 v[26:27], v[20:21], v[40:41], v[84:85] op_sel_hi:[1,0,1]
	ds_read_b128 v[18:21], v18
	v_pk_fma_f32 v[100:101], v[22:23], v[40:41], v[86:87] op_sel_hi:[1,0,1]
	v_pk_fma_f32 v[104:105], v[30:31], v[40:41], v[94:95] op_sel_hi:[1,0,1]
	v_pk_fma_f32 v[28:29], v[28:29], v[40:41], v[92:93] op_sel_hi:[1,0,1]
	v_pk_fma_f32 v[62:63], v[24:25], v[40:41], v[88:89] op_sel_hi:[1,0,1]
	s_waitcnt lgkmcnt(0)
	v_mov_b32_e32 v22, v19
	v_mov_b32_e32 v23, v20
	v_mov_b32_e32 v19, v21
	v_pk_add_f32 v[18:19], v[22:23], v[18:19]
	s_nop 0
	v_add_f32_e32 v18, v18, v19
	v_mov_b32_e32 v19, v18
	s_nop 1
	v_permlane16_swap_b32_e32 v18, v19
	s_waitcnt lgkmcnt(0)
	v_add_f32_e32 v18, v18, v19
	v_mov_b32_e32 v19, v18
	s_nop 1
	v_permlane32_swap_b32_e32 v18, v19
	s_waitcnt lgkmcnt(0)
	v_add_f32_e32 v18, v18, v19
	v_fmamk_f32 v18, v18, 0x3a800000, v212
	v_rsq_f32_e32 v18, v18
	s_nop 0
	v_pk_fma_f32 v[112:113], v[16:17], v[18:19], v[96:97] op_sel_hi:[1,0,1]
	v_pk_fma_f32 v[120:121], v[14:15], v[18:19], v[94:95] op_sel_hi:[1,0,1]
	v_pk_fma_f32 v[40:41], v[12:13], v[18:19], v[92:93] op_sel_hi:[1,0,1]
	v_pk_fma_f32 v[48:49], v[10:11], v[18:19], v[90:91] op_sel_hi:[1,0,1]
	v_pk_fma_f32 v[74:75], v[8:9], v[18:19], v[88:89] op_sel_hi:[1,0,1]
	v_pk_fma_f32 v[114:115], v[6:7], v[18:19], v[86:87] op_sel_hi:[1,0,1]
	v_pk_fma_f32 v[30:31], v[4:5], v[18:19], v[84:85] op_sel_hi:[1,0,1]
	v_pk_fma_f32 v[46:47], v[2:3], v[18:19], v[82:83] op_sel_hi:[1,0,1]
	s_cbranch_scc1 .LBB0_1333
	ds_read_b128 v[2:5], v218 offset:1024
	ds_read_b128 v[6:9], v218 offset:1040
	ds_read_b128 v[18:21], v218 offset:1536
	ds_read_b128 v[22:25], v218 offset:1552
	v_cmp_gt_i32_e32 vcc, s1, v198
	s_waitcnt lgkmcnt(0)
	v_sub_f32_e32 v11, v3, v95
	v_sub_f32_e32 v10, v2, v94
	v_sub_f32_e32 v17, v5, v97
	v_sub_f32_e32 v16, v4, v96
	v_sub_f32_e32 v5, v7, v91
	v_sub_f32_e32 v4, v6, v90
	v_sub_f32_e32 v15, v9, v93
	v_sub_f32_e32 v14, v8, v92
	v_sub_f32_e32 v9, v19, v87
	v_sub_f32_e32 v8, v18, v86
	v_sub_f32_e32 v13, v21, v89
	v_sub_f32_e32 v12, v20, v88
	v_sub_f32_e32 v3, v23, v83
	v_sub_f32_e32 v2, v22, v82
	v_sub_f32_e32 v7, v25, v85
	v_sub_f32_e32 v6, v24, v84
	v_cndmask_b32_e64 v18, 1.0, 0, vcc
	v_cmp_gt_i32_e32 vcc, s1, v199
	v_pk_fma_f32 v[146:147], v[18:19], v[16:17], v[146:147] op_sel_hi:[0,1,1]
	v_pk_fma_f32 v[166:167], v[18:19], v[10:11], v[166:167] op_sel_hi:[0,1,1]
	v_pk_fma_f32 v[142:143], v[18:19], v[14:15], v[142:143] op_sel_hi:[0,1,1]
	v_pk_fma_f32 v[140:141], v[18:19], v[4:5], v[140:141] op_sel_hi:[0,1,1]
	v_pk_fma_f32 v[138:139], v[18:19], v[12:13], v[138:139] op_sel_hi:[0,1,1]
	v_pk_fma_f32 v[162:163], v[18:19], v[8:9], v[162:163] op_sel_hi:[0,1,1]
	v_pk_fma_f32 v[134:135], v[18:19], v[6:7], v[134:135] op_sel_hi:[0,1,1]
	v_pk_fma_f32 v[132:133], v[18:19], v[2:3], v[132:133] op_sel_hi:[0,1,1]
	v_cndmask_b32_e64 v18, 1.0, 0, vcc
	v_cmp_gt_i32_e32 vcc, s1, v213
	v_pk_fma_f32 v[164:165], v[18:19], v[16:17], v[164:165] op_sel_hi:[0,1,1]
	v_pk_fma_f32 v[174:175], v[18:19], v[10:11], v[174:175] op_sel_hi:[0,1,1]
	v_pk_fma_f32 v[126:127], v[18:19], v[14:15], v[126:127] op_sel_hi:[0,1,1]
	v_pk_fma_f32 v[124:125], v[18:19], v[4:5], v[124:125] op_sel_hi:[0,1,1]
	v_pk_fma_f32 v[136:137], v[18:19], v[12:13], v[136:137] op_sel_hi:[0,1,1]
	v_pk_fma_f32 v[172:173], v[18:19], v[8:9], v[172:173] op_sel_hi:[0,1,1]
	v_pk_fma_f32 v[118:119], v[18:19], v[6:7], v[118:119] op_sel_hi:[0,1,1]
	v_pk_fma_f32 v[116:117], v[18:19], v[2:3], v[116:117] op_sel_hi:[0,1,1]
	v_cndmask_b32_e64 v18, 1.0, 0, vcc
	v_cmp_gt_i32_e32 vcc, s1, v214
	v_pk_fma_f32 v[168:169], v[18:19], v[16:17], v[168:169] op_sel_hi:[0,1,1]
	v_pk_fma_f32 v[178:179], v[18:19], v[10:11], v[178:179] op_sel_hi:[0,1,1]
	v_pk_fma_f32 v[110:111], v[18:19], v[14:15], v[110:111] op_sel_hi:[0,1,1]
	v_pk_fma_f32 v[108:109], v[18:19], v[4:5], v[108:109] op_sel_hi:[0,1,1]
	v_pk_fma_f32 v[144:145], v[18:19], v[12:13], v[144:145] op_sel_hi:[0,1,1]
	v_pk_fma_f32 v[176:177], v[18:19], v[8:9], v[176:177] op_sel_hi:[0,1,1]
	v_pk_fma_f32 v[102:103], v[18:19], v[6:7], v[102:103] op_sel_hi:[0,1,1]
	v_pk_fma_f32 v[106:107], v[18:19], v[2:3], v[106:107] op_sel_hi:[0,1,1]
	v_cndmask_b32_e64 v18, 1.0, 0, vcc
	v_cmp_gt_i32_e32 vcc, s1, v190
	v_pk_fma_f32 v[180:181], v[18:19], v[16:17], v[180:181] op_sel_hi:[0,1,1]
	v_pk_fma_f32 v[184:185], v[18:19], v[10:11], v[184:185] op_sel_hi:[0,1,1]
	v_pk_fma_f32 v[122:123], v[18:19], v[14:15], v[122:123] op_sel_hi:[0,1,1]
	v_pk_fma_f32 v[130:131], v[18:19], v[4:5], v[130:131] op_sel_hi:[0,1,1]
	v_pk_fma_f32 v[170:171], v[18:19], v[12:13], v[170:171] op_sel_hi:[0,1,1]
	v_pk_fma_f32 v[182:183], v[18:19], v[8:9], v[182:183] op_sel_hi:[0,1,1]
	v_pk_fma_f32 v[80:81], v[18:19], v[6:7], v[80:81] op_sel_hi:[0,1,1]
	v_pk_fma_f32 v[128:129], v[18:19], v[2:3], v[128:129] op_sel_hi:[0,1,1]
	v_cndmask_b32_e64 v18, 1.0, 0, vcc
	v_cmp_gt_i32_e32 vcc, s1, v191
	v_pk_fma_f32 v[64:65], v[18:19], v[16:17], v[64:65] op_sel_hi:[0,1,1]
	v_pk_fma_f32 v[70:71], v[18:19], v[10:11], v[70:71] op_sel_hi:[0,1,1]
	v_pk_fma_f32 v[60:61], v[18:19], v[14:15], v[60:61] op_sel_hi:[0,1,1]
	v_pk_fma_f32 v[58:59], v[18:19], v[4:5], v[58:59] op_sel_hi:[0,1,1]
	v_pk_fma_f32 v[56:57], v[18:19], v[12:13], v[56:57] op_sel_hi:[0,1,1]
	v_pk_fma_f32 v[66:67], v[18:19], v[8:9], v[66:67] op_sel_hi:[0,1,1]
	v_pk_fma_f32 v[52:53], v[18:19], v[6:7], v[52:53] op_sel_hi:[0,1,1]
	v_pk_fma_f32 v[50:51], v[18:19], v[2:3], v[50:51] op_sel_hi:[0,1,1]
	v_cndmask_b32_e64 v18, 1.0, 0, vcc
	v_cmp_gt_i32_e32 vcc, s1, v193
	v_pk_fma_f32 v[68:69], v[18:19], v[16:17], v[68:69] op_sel_hi:[0,1,1]
	v_pk_fma_f32 v[78:79], v[18:19], v[10:11], v[78:79] op_sel_hi:[0,1,1]
	v_pk_fma_f32 v[44:45], v[18:19], v[14:15], v[44:45] op_sel_hi:[0,1,1]
	v_pk_fma_f32 v[42:43], v[18:19], v[4:5], v[42:43] op_sel_hi:[0,1,1]
	v_pk_fma_f32 v[54:55], v[18:19], v[12:13], v[54:55] op_sel_hi:[0,1,1]
	v_pk_fma_f32 v[76:77], v[18:19], v[8:9], v[76:77] op_sel_hi:[0,1,1]
	v_pk_fma_f32 v[36:37], v[18:19], v[6:7], v[36:37] op_sel_hi:[0,1,1]
	v_pk_fma_f32 v[34:35], v[18:19], v[2:3], v[34:35] op_sel_hi:[0,1,1]
	v_cndmask_b32_e64 v18, 1.0, 0, vcc
	v_cmp_gt_i32_e32 vcc, s1, v195
	v_pk_fma_f32 v[72:73], v[18:19], v[16:17], v[72:73] op_sel_hi:[0,1,1]
	v_pk_fma_f32 v[104:105], v[18:19], v[10:11], v[104:105] op_sel_hi:[0,1,1]
	v_pk_fma_f32 v[28:29], v[18:19], v[14:15], v[28:29] op_sel_hi:[0,1,1]
	v_pk_fma_f32 v[38:39], v[18:19], v[4:5], v[38:39] op_sel_hi:[0,1,1]
	v_pk_fma_f32 v[62:63], v[18:19], v[12:13], v[62:63] op_sel_hi:[0,1,1]
	v_pk_fma_f32 v[100:101], v[18:19], v[8:9], v[100:101] op_sel_hi:[0,1,1]
	v_pk_fma_f32 v[26:27], v[18:19], v[6:7], v[26:27] op_sel_hi:[0,1,1]
	v_pk_fma_f32 v[32:33], v[18:19], v[2:3], v[32:33] op_sel_hi:[0,1,1]
	v_cndmask_b32_e64 v18, 1.0, 0, vcc
	v_pk_fma_f32 v[112:113], v[18:19], v[16:17], v[112:113] op_sel_hi:[0,1,1]
	v_pk_fma_f32 v[120:121], v[18:19], v[10:11], v[120:121] op_sel_hi:[0,1,1]
	v_pk_fma_f32 v[40:41], v[18:19], v[14:15], v[40:41] op_sel_hi:[0,1,1]
	v_pk_fma_f32 v[48:49], v[18:19], v[4:5], v[48:49] op_sel_hi:[0,1,1]
	v_pk_fma_f32 v[74:75], v[18:19], v[12:13], v[74:75] op_sel_hi:[0,1,1]
	v_pk_fma_f32 v[114:115], v[18:19], v[8:9], v[114:115] op_sel_hi:[0,1,1]
	v_pk_fma_f32 v[30:31], v[18:19], v[6:7], v[30:31] op_sel_hi:[0,1,1]
	v_pk_fma_f32 v[46:47], v[18:19], v[2:3], v[46:47] op_sel_hi:[0,1,1]

.LBB0_1344:
	v_add_u32_e32 v83, -1, v215
	v_add_u32_e32 v84, 1, v215
	v_and_b32_e32 v82, 48, v215
	v_and_b32_e32 v83, 15, v83
	v_and_b32_e32 v84, 15, v84
	v_cmp_eq_u32_e64 s[42:43], 15, v216
	v_or3_b32 v83, v83, v82, v217
	v_or3_b32 v82, v84, v82, v217
	v_lshlrev_b32_e32 v215, 2, v83
	v_lshlrev_b32_e32 v216, 2, v82
	s_movk_i32 s1, 0x4000
	s_waitcnt lgkmcnt(0)
	v_cndmask_b32_e64 v18, v166, v18, s[42:43]
	v_cndmask_b32_e64 v19, v167, v19, s[42:43]
	v_cndmask_b32_e64 v84, v174, v166, s[42:43]
	v_cndmask_b32_e64 v85, v174, v178, s[40:41]
	v_cmp_gt_i32_e32 vcc, s1, v198
	v_mov_b32_dpp v18, v18 row_ror:1 row_mask:0xf bank_mask:0xf
	v_mov_b32_dpp v19, v19 row_ror:1 row_mask:0xf bank_mask:0xf
	v_mov_b32_dpp v86, v84 row_ror:1 row_mask:0xf bank_mask:0xf
	v_mov_b32_dpp v88, v85 row_ror:15 row_mask:0xf bank_mask:0xf
	v_cndmask_b32_e64 v84, v175, v167, s[42:43]
	v_cndmask_b32_e64 v85, v175, v179, s[40:41]
	v_cndmask_b32_e32 v82, v202, v200, vcc
	v_mov_b32_dpp v87, v84 row_ror:1 row_mask:0xf bank_mask:0xf
	v_mov_b32_dpp v89, v85 row_ror:15 row_mask:0xf bank_mask:0xf
	v_and_b32_e32 v83, v82, v198
	v_cmp_gt_i32_e32 vcc, s1, v199
	v_cndmask_b32_e64 v84, v178, v174, s[42:43]
	v_cmp_eq_u32_e64 s[44:45], v83, v82
	v_cndmask_b32_e32 v82, v202, v200, vcc
	v_cndmask_b32_e64 v85, v178, v184, s[40:41]
	v_mov_b32_dpp v90, v84 row_ror:1 row_mask:0xf bank_mask:0xf
	v_cndmask_b32_e64 v84, v179, v175, s[42:43]
	v_cmp_eq_u32_e64 s[58:59], 0, v83
	v_and_b32_e32 v83, v82, v199
	v_mov_b32_dpp v91, v85 row_ror:15 row_mask:0xf bank_mask:0xf
	v_cndmask_b32_e64 v85, v179, v185, s[40:41]
	v_mov_b32_dpp v92, v84 row_ror:1 row_mask:0xf bank_mask:0xf
	v_cndmask_b32_e64 v84, v184, v178, s[42:43]
	v_cmp_eq_u32_e64 s[48:49], 0, v83
	v_cmp_eq_u32_e64 s[46:47], v83, v82
	v_mov_b32_dpp v93, v85 row_ror:15 row_mask:0xf bank_mask:0xf
	v_mov_b32_dpp v96, v84 row_ror:1 row_mask:0xf bank_mask:0xf
	s_waitcnt lgkmcnt(0)
	v_cndmask_b32_e64 v19, v19, 0, s[58:59]
	v_cndmask_b32_e64 v18, v18, 0, s[58:59]
	v_pk_mul_f32 v[84:85], v[166:167], v[22:23]
	v_cmp_gt_i32_e32 vcc, s1, v213
	v_pk_fma_f32 v[18:19], v[2:3], v[18:19], v[84:85]
	v_cndmask_b32_e64 v85, v87, 0, s[48:49]
	v_cndmask_b32_e64 v84, v86, 0, s[48:49]
	v_cndmask_b32_e64 v87, v89, 0, s[46:47]
	v_cndmask_b32_e64 v86, v88, 0, s[46:47]
	v_pk_mul_f32 v[88:89], v[174:175], v[22:23]
	v_cndmask_b32_e32 v82, v202, v200, vcc
	v_pk_fma_f32 v[84:85], v[2:3], v[84:85], v[88:89]
	v_and_b32_e32 v83, v82, v213
	v_pk_fma_f32 v[84:85], v[6:7], v[86:87], v[84:85]
	v_cmp_eq_u32_e64 s[52:53], 0, v83
	v_pk_add_f32 v[84:85], v[10:11], v[84:85]
	v_cmp_eq_u32_e64 s[50:51], v83, v82
	v_mul_f32_e32 v86, 0xbfb8aa3b, v84
	v_mul_f32_e32 v87, 0xbfb8aa3b, v85
	v_exp_f32_e32 v86, v86
	v_exp_f32_e32 v87, v87
	v_cndmask_b32_e64 v88, v91, 0, s[50:51]
	v_cndmask_b32_e64 v89, v93, 0, s[50:51]
	v_cndmask_b32_e64 v14, v184, v14, s[40:41]
	v_pk_add_f32 v[86:87], v[86:87], 1.0 op_sel_hi:[1,0]
	v_cmp_gt_i32_e32 vcc, s1, v214
	v_rcp_f32_e32 v86, v86
	v_rcp_f32_e32 v87, v87
	v_mov_b32_dpp v97, v14 row_ror:15 row_mask:0xf bank_mask:0xf
	v_cndmask_b32_e64 v14, v185, v179, s[42:43]
	v_cndmask_b32_e32 v82, v202, v200, vcc
	v_pk_mul_f32 v[84:85], v[84:85], v[86:87]
	v_cndmask_b32_e64 v87, v92, 0, s[52:53]
	v_cndmask_b32_e64 v86, v90, 0, s[52:53]
	v_pk_mul_f32 v[90:91], v[178:179], v[22:23]
	v_cndmask_b32_e64 v15, v185, v15, s[40:41]
	v_pk_fma_f32 v[86:87], v[2:3], v[86:87], v[90:91]
	v_mov_b32_dpp v204, v14 row_ror:1 row_mask:0xf bank_mask:0xf
	v_pk_fma_f32 v[86:87], v[6:7], v[88:89], v[86:87]
	v_and_b32_e32 v83, v82, v214
	v_pk_add_f32 v[86:87], v[10:11], v[86:87]
	v_mov_b32_dpp v205, v15 row_ror:15 row_mask:0xf bank_mask:0xf
	v_mul_f32_e32 v88, 0xbfb8aa3b, v86
	v_mul_f32_e32 v89, 0xbfb8aa3b, v87
	v_exp_f32_e32 v88, v88
	v_exp_f32_e32 v89, v89
	v_cmp_eq_u32_e64 s[54:55], 0, v83
	v_cmp_eq_u32_e64 s[56:57], v83, v82
	v_cndmask_b32_e64 v82, v166, v174, s[40:41]
	v_pk_add_f32 v[88:89], v[88:89], 1.0 op_sel_hi:[1,0]
	v_cndmask_b32_e64 v83, v167, v175, s[40:41]
	v_rcp_f32_e32 v88, v88
	v_rcp_f32_e32 v89, v89
	v_mov_b32_dpp v82, v82 row_ror:15 row_mask:0xf bank_mask:0xf
	v_mov_b32_dpp v83, v83 row_ror:15 row_mask:0xf bank_mask:0xf
	v_pk_mul_f32 v[22:23], v[184:185], v[22:23]
	v_pk_mul_f32 v[86:87], v[86:87], v[88:89]
	s_waitcnt lgkmcnt(0)
	v_cndmask_b32_e64 v89, v204, 0, s[54:55]
	v_cndmask_b32_e64 v88, v96, 0, s[54:55]
	v_cndmask_b32_e64 v91, v205, 0, s[56:57]
	v_cndmask_b32_e64 v90, v97, 0, s[56:57]
	v_pk_fma_f32 v[2:3], v[2:3], v[88:89], v[22:23]
	v_cndmask_b32_e64 v83, v83, 0, s[44:45]
	v_pk_fma_f32 v[2:3], v[6:7], v[90:91], v[2:3]
	v_cndmask_b32_e64 v82, v82, 0, s[44:45]
	v_pk_add_f32 v[2:3], v[10:11], v[2:3]
	v_pk_fma_f32 v[18:19], v[6:7], v[82:83], v[18:19]
	v_mul_f32_e32 v6, 0xbfb8aa3b, v2
	v_mul_f32_e32 v7, 0xbfb8aa3b, v3
	v_exp_f32_e32 v6, v6
	v_exp_f32_e32 v7, v7
	v_pk_mul_f32 v[14:15], v[146:147], v[24:25]
	v_pk_add_f32 v[18:19], v[10:11], v[18:19]
	v_cndmask_b32_e64 v10, v164, v146, s[42:43]
	v_pk_add_f32 v[6:7], v[6:7], 1.0 op_sel_hi:[1,0]
	v_mul_f32_e32 v82, 0xbfb8aa3b, v18
	v_rcp_f32_e32 v6, v6
	v_rcp_f32_e32 v7, v7
	v_mul_f32_e32 v83, 0xbfb8aa3b, v19
	v_exp_f32_e32 v82, v82
	v_exp_f32_e32 v83, v83
	v_pk_mul_f32 v[2:3], v[2:3], v[6:7]
	v_cndmask_b32_e64 v7, v147, v165, s[40:41]
	v_pk_mul_f32 v[88:89], v[182:183], v[2:3]
	v_cndmask_b32_e64 v3, v146, v164, s[40:41]
	v_cndmask_b32_e64 v2, v146, v20, s[42:43]
	s_nop 0
	v_mov_b32_dpp v6, v3 row_ror:15 row_mask:0xf bank_mask:0xf
	v_cndmask_b32_e64 v3, v147, v21, s[42:43]
	v_mov_b32_dpp v2, v2 row_ror:1 row_mask:0xf bank_mask:0xf
	s_nop 0
	v_mov_b32_dpp v3, v3 row_ror:1 row_mask:0xf bank_mask:0xf
	v_mov_b32_dpp v7, v7 row_ror:15 row_mask:0xf bank_mask:0xf
	s_waitcnt lgkmcnt(0)
	v_cndmask_b32_e64 v6, v6, 0, s[44:45]
	v_pk_add_f32 v[82:83], v[82:83], 1.0 op_sel_hi:[1,0]
	v_cndmask_b32_e64 v2, v2, 0, s[58:59]
	v_cndmask_b32_e64 v3, v3, 0, s[58:59]
	v_cndmask_b32_e64 v7, v7, 0, s[44:45]
	v_pk_fma_f32 v[2:3], v[4:5], v[2:3], v[14:15]
	v_cndmask_b32_e64 v20, v165, v147, s[42:43]
	v_pk_fma_f32 v[2:3], v[8:9], v[6:7], v[2:3]
	v_rcp_f32_e32 v82, v82
	v_pk_add_f32 v[2:3], v[12:13], v[2:3]
	v_rcp_f32_e32 v83, v83
	v_mul_f32_e32 v6, 0xbfb8aa3b, v2
	v_mul_f32_e32 v7, 0xbfb8aa3b, v3
	v_exp_f32_e32 v6, v6
	v_exp_f32_e32 v7, v7
	v_cndmask_b32_e64 v11, v164, v168, s[40:41]
	v_mov_b32_dpp v10, v10 row_ror:1 row_mask:0xf bank_mask:0xf
	v_cndmask_b32_e64 v21, v165, v169, s[40:41]
	v_pk_add_f32 v[6:7], v[6:7], 1.0 op_sel_hi:[1,0]
	v_mov_b32_dpp v20, v20 row_ror:1 row_mask:0xf bank_mask:0xf
	v_rcp_f32_e32 v6, v6
	v_rcp_f32_e32 v7, v7
	v_mov_b32_dpp v11, v11 row_ror:15 row_mask:0xf bank_mask:0xf
	v_mov_b32_dpp v21, v21 row_ror:15 row_mask:0xf bank_mask:0xf
	v_cndmask_b32_e64 v90, v169, v165, s[42:43]
	s_nop 1
	v_mov_b32_dpp v96, v90 row_ror:1 row_mask:0xf bank_mask:0xf
	v_cndmask_b32_e64 v90, v180, v168, s[42:43]
	v_pk_mul_f32 v[18:19], v[18:19], v[82:83]
	v_cndmask_b32_e64 v91, v169, v181, s[40:41]
	v_mov_b32_dpp v146, v90 row_ror:1 row_mask:0xf bank_mask:0xf
	v_cndmask_b32_e64 v90, v181, v169, s[42:43]
	v_pk_mul_f32 v[2:3], v[2:3], v[6:7]
	v_pk_mul_f32 v[82:83], v[162:163], v[18:19]
	v_pk_mul_f32 v[18:19], v[164:165], v[24:25]
	v_mov_b32_dpp v97, v91 row_ror:15 row_mask:0xf bank_mask:0xf
	v_mov_b32_dpp v147, v90 row_ror:1 row_mask:0xf bank_mask:0xf
	v_pk_mul_f32 v[90:91], v[138:139], v[2:3]
	s_waitcnt lgkmcnt(0)
	v_cndmask_b32_e64 v3, v20, 0, s[48:49]
	v_cndmask_b32_e64 v2, v10, 0, s[48:49]
	v_cndmask_b32_e64 v7, v21, 0, s[46:47]
	v_cndmask_b32_e64 v6, v11, 0, s[46:47]
	v_pk_fma_f32 v[2:3], v[4:5], v[2:3], v[18:19]
	v_cndmask_b32_e64 v22, v168, v164, s[42:43]
	v_pk_fma_f32 v[2:3], v[8:9], v[6:7], v[2:3]
	v_cndmask_b32_e64 v23, v168, v180, s[40:41]
	v_pk_add_f32 v[2:3], v[12:13], v[2:3]
	v_mov_b32_dpp v22, v22 row_ror:1 row_mask:0xf bank_mask:0xf
	v_mul_f32_e32 v6, 0xbfb8aa3b, v2
	v_mul_f32_e32 v7, 0xbfb8aa3b, v3
	v_exp_f32_e32 v6, v6
	v_exp_f32_e32 v7, v7
	v_mov_b32_dpp v23, v23 row_ror:15 row_mask:0xf bank_mask:0xf
	v_pk_mul_f32 v[94:95], v[168:169], v[24:25]
	v_cndmask_b32_e64 v16, v180, v16, s[40:41]
	v_pk_add_f32 v[6:7], v[6:7], 1.0 op_sel_hi:[1,0]
	v_cndmask_b32_e64 v17, v181, v17, s[40:41]
	v_rcp_f32_e32 v6, v6
	v_rcp_f32_e32 v7, v7
	v_mov_b32_dpp v16, v16 row_ror:15 row_mask:0xf bank_mask:0xf
	v_mov_b32_dpp v17, v17 row_ror:15 row_mask:0xf bank_mask:0xf
	v_pk_mul_f32 v[24:25], v[180:181], v[24:25]
	v_pk_mul_f32 v[2:3], v[2:3], v[6:7]
	v_cndmask_b32_e64 v7, v97, 0, s[50:51]
	v_pk_mul_f32 v[92:93], v[136:137], v[2:3]
	v_cndmask_b32_e64 v3, v96, 0, s[52:53]
	s_waitcnt lgkmcnt(0)
	v_cndmask_b32_e64 v2, v22, 0, s[52:53]
	v_cndmask_b32_e64 v6, v23, 0, s[50:51]
	v_pk_fma_f32 v[2:3], v[4:5], v[2:3], v[94:95]
	v_pk_mul_f32 v[84:85], v[172:173], v[84:85]
	v_pk_fma_f32 v[2:3], v[8:9], v[6:7], v[2:3]
	v_pk_mul_f32 v[86:87], v[176:177], v[86:87]
	v_pk_add_f32 v[2:3], v[12:13], v[2:3]
	v_mov_b32_e32 v14, 0
	v_mul_f32_e32 v6, 0xbfb8aa3b, v2
	v_mul_f32_e32 v7, 0xbfb8aa3b, v3
	v_exp_f32_e32 v6, v6
	v_exp_f32_e32 v7, v7
	s_and_b64 vcc, exec, s[60:61]
	v_mov_b32_e32 v18, 0
	v_mov_b32_e32 v19, 0
	v_pk_add_f32 v[6:7], v[6:7], 1.0 op_sel_hi:[1,0]
	v_mov_b32_e32 v20, 0
	v_rcp_f32_e32 v6, v6
	v_rcp_f32_e32 v7, v7
	v_mov_b32_e32 v21, 0
	v_pk_mul_f32 v[2:3], v[2:3], v[6:7]
	s_nop 0
	v_pk_mul_f32 v[94:95], v[144:145], v[2:3]
	v_cndmask_b32_e64 v3, v147, 0, s[54:55]
	v_cndmask_b32_e64 v2, v146, 0, s[54:55]
	v_cndmask_b32_e64 v7, v17, 0, s[56:57]
	v_cndmask_b32_e64 v6, v16, 0, s[56:57]
	v_pk_fma_f32 v[2:3], v[4:5], v[2:3], v[24:25]
	s_nop 0
	v_pk_fma_f32 v[2:3], v[8:9], v[6:7], v[2:3]
	s_nop 0
	v_pk_add_f32 v[2:3], v[12:13], v[2:3]
	s_nop 0
	v_mul_f32_e32 v4, 0xbfb8aa3b, v2
	v_mul_f32_e32 v5, 0xbfb8aa3b, v3
	v_exp_f32_e32 v4, v4
	v_exp_f32_e32 v5, v5
	s_nop 0
	v_pk_add_f32 v[4:5], v[4:5], 1.0 op_sel_hi:[1,0]
	s_nop 0
	v_rcp_f32_e32 v4, v4
	v_rcp_f32_e32 v5, v5
	s_nop 0
	v_pk_mul_f32 v[2:3], v[2:3], v[4:5]
	s_nop 0
	v_pk_mul_f32 v[96:97], v[170:171], v[2:3]
	s_nop 0
	ds_read_b128 v[2:5], v219 offset:16
	ds_read_b128 v[22:25], v220 offset:16
	ds_read_b128 v[6:9], v221 offset:16
	ds_read_b128 v[10:13], v222 offset:16
	s_cbranch_vccnz .LBB0_1346
	ds_read_b128 v[18:21], v218 offset:16

.LBB0_1348:
	s_waitcnt lgkmcnt(0)
	v_cndmask_b32_e64 v18, v140, v18, s[42:43]
	v_cndmask_b32_e64 v19, v141, v19, s[42:43]
	v_cndmask_b32_e64 v136, v140, v124, s[40:41]
	v_mov_b32_dpp v18, v18 row_ror:1 row_mask:0xf bank_mask:0xf
	v_cndmask_b32_e64 v137, v141, v125, s[40:41]
	v_mov_b32_dpp v19, v19 row_ror:1 row_mask:0xf bank_mask:0xf
	v_mov_b32_dpp v136, v136 row_ror:15 row_mask:0xf bank_mask:0xf
	v_mov_b32_dpp v137, v137 row_ror:15 row_mask:0xf bank_mask:0xf
	v_cndmask_b32_e64 v14, v130, v14, s[40:41]
	s_nop 1
	v_mov_b32_dpp v166, v14 row_ror:15 row_mask:0xf bank_mask:0xf
	v_cndmask_b32_e64 v14, v131, v109, s[42:43]
	v_cndmask_b32_e64 v15, v131, v15, s[40:41]
	v_cndmask_b32_e64 v139, v124, v140, s[42:43]
	v_cndmask_b32_e64 v145, v125, v141, s[42:43]
	v_mov_b32_dpp v167, v14 row_ror:1 row_mask:0xf bank_mask:0xf
	v_mov_b32_dpp v168, v15 row_ror:15 row_mask:0xf bank_mask:0xf
	s_waitcnt lgkmcnt(0)
	v_cndmask_b32_e64 v15, v19, 0, s[58:59]
	v_cndmask_b32_e64 v14, v18, 0, s[58:59]
	v_pk_mul_f32 v[140:141], v[140:141], v[22:23]
	v_cndmask_b32_e64 v19, v137, 0, s[44:45]
	v_cndmask_b32_e64 v18, v136, 0, s[44:45]
	v_pk_fma_f32 v[14:15], v[2:3], v[14:15], v[140:141]
	v_cndmask_b32_e64 v144, v124, v108, s[40:41]
	v_pk_fma_f32 v[14:15], v[6:7], v[18:19], v[14:15]
	v_mov_b32_dpp v139, v139 row_ror:1 row_mask:0xf bank_mask:0xf
	v_pk_add_f32 v[14:15], v[10:11], v[14:15]
	v_cndmask_b32_e64 v146, v125, v109, s[40:41]
	v_mul_f32_e32 v18, 0xbfb8aa3b, v14
	v_mul_f32_e32 v19, 0xbfb8aa3b, v15
	v_exp_f32_e32 v18, v18
	v_exp_f32_e32 v19, v19
	v_mov_b32_dpp v145, v145 row_ror:1 row_mask:0xf bank_mask:0xf
	v_mov_b32_dpp v144, v144 row_ror:15 row_mask:0xf bank_mask:0xf
	v_mov_b32_dpp v146, v146 row_ror:15 row_mask:0xf bank_mask:0xf
	v_pk_add_f32 v[18:19], v[18:19], 1.0 op_sel_hi:[1,0]
	v_cndmask_b32_e64 v147, v108, v124, s[42:43]
	v_rcp_f32_e32 v18, v18
	v_rcp_f32_e32 v19, v19
	v_cndmask_b32_e64 v163, v109, v125, s[42:43]
	v_pk_mul_f32 v[124:125], v[124:125], v[22:23]
	s_waitcnt lgkmcnt(0)
	v_cndmask_b32_e64 v141, v146, 0, s[46:47]
	v_pk_mul_f32 v[14:15], v[14:15], v[18:19]
	v_cndmask_b32_e64 v19, v145, 0, s[48:49]
	v_cndmask_b32_e64 v18, v139, 0, s[48:49]
	v_cndmask_b32_e64 v140, v144, 0, s[46:47]
	v_pk_fma_f32 v[18:19], v[2:3], v[18:19], v[124:125]
	v_cndmask_b32_e64 v162, v108, v130, s[40:41]
	v_pk_fma_f32 v[18:19], v[6:7], v[140:141], v[18:19]
	v_mov_b32_dpp v147, v147 row_ror:1 row_mask:0xf bank_mask:0xf
	v_pk_add_f32 v[18:19], v[10:11], v[18:19]
	v_cndmask_b32_e64 v164, v109, v131, s[40:41]
	v_mul_f32_e32 v124, 0xbfb8aa3b, v18
	v_mul_f32_e32 v125, 0xbfb8aa3b, v19
	v_exp_f32_e32 v124, v124
	v_exp_f32_e32 v125, v125
	v_mov_b32_dpp v163, v163 row_ror:1 row_mask:0xf bank_mask:0xf
	v_mov_b32_dpp v162, v162 row_ror:15 row_mask:0xf bank_mask:0xf
	v_mov_b32_dpp v164, v164 row_ror:15 row_mask:0xf bank_mask:0xf
	v_pk_add_f32 v[124:125], v[124:125], 1.0 op_sel_hi:[1,0]
	v_cndmask_b32_e64 v165, v130, v108, s[42:43]
	v_rcp_f32_e32 v124, v124
	v_rcp_f32_e32 v125, v125
	v_pk_mul_f32 v[108:109], v[108:109], v[22:23]
	v_mov_b32_dpp v165, v165 row_ror:1 row_mask:0xf bank_mask:0xf
	v_pk_mul_f32 v[22:23], v[130:131], v[22:23]
	v_pk_mul_f32 v[18:19], v[18:19], v[124:125]
	s_waitcnt lgkmcnt(0)
	v_cndmask_b32_e64 v125, v164, 0, s[50:51]
	v_pk_mul_f32 v[18:19], v[116:117], v[18:19]
	v_cndmask_b32_e64 v117, v163, 0, s[52:53]
	v_cndmask_b32_e64 v116, v147, 0, s[52:53]
	v_cndmask_b32_e64 v124, v162, 0, s[50:51]
	v_pk_fma_f32 v[108:109], v[2:3], v[116:117], v[108:109]
	v_pk_mul_f32 v[136:137], v[142:143], v[24:25]
	v_pk_fma_f32 v[108:109], v[6:7], v[124:125], v[108:109]
	v_cndmask_b32_e64 v16, v122, v16, s[40:41]
	v_pk_add_f32 v[108:109], v[10:11], v[108:109]
	v_pk_mul_f32 v[14:15], v[132:133], v[14:15]
	v_mul_f32_e32 v116, 0xbfb8aa3b, v108
	v_mul_f32_e32 v117, 0xbfb8aa3b, v109
	v_exp_f32_e32 v116, v116
	v_exp_f32_e32 v117, v117
	v_pk_mul_f32 v[132:133], v[126:127], v[24:25]
	v_pk_mul_f32 v[140:141], v[110:111], v[24:25]
	v_pk_mul_f32 v[24:25], v[122:123], v[24:25]
	v_pk_add_f32 v[116:117], v[116:117], 1.0 op_sel_hi:[1,0]
	v_cndmask_b32_e64 v17, v123, v17, s[40:41]
	v_rcp_f32_e32 v116, v116
	v_rcp_f32_e32 v117, v117
	v_lshl_or_b32 v138, s0, 7, v197
	s_movk_i32 s0, 0xfe
	v_pk_mul_f32 v[108:109], v[108:109], v[116:117]
	s_nop 0
	v_pk_mul_f32 v[106:107], v[106:107], v[108:109]
	v_cndmask_b32_e64 v109, v167, 0, s[54:55]
	v_cndmask_b32_e64 v108, v165, 0, s[54:55]
	v_cndmask_b32_e64 v117, v168, 0, s[56:57]
	v_cndmask_b32_e64 v116, v166, 0, s[56:57]
	v_pk_fma_f32 v[2:3], v[2:3], v[108:109], v[22:23]
	v_cndmask_b32_e64 v22, v127, v143, s[42:43]
	v_pk_fma_f32 v[2:3], v[6:7], v[116:117], v[2:3]
	v_cndmask_b32_e64 v23, v127, v111, s[40:41]
	v_pk_add_f32 v[2:3], v[10:11], v[2:3]
	v_cndmask_b32_e64 v11, v143, v127, s[40:41]
	v_mul_f32_e32 v6, 0xbfb8aa3b, v2
	v_mul_f32_e32 v7, 0xbfb8aa3b, v3
	v_exp_f32_e32 v6, v6
	v_exp_f32_e32 v7, v7
	v_mov_b32_dpp v11, v11 row_ror:15 row_mask:0xf bank_mask:0xf
	v_mov_b32_dpp v22, v22 row_ror:1 row_mask:0xf bank_mask:0xf
	v_mov_b32_dpp v23, v23 row_ror:15 row_mask:0xf bank_mask:0xf
	v_pk_add_f32 v[6:7], v[6:7], 1.0 op_sel_hi:[1,0]
	v_cndmask_b32_e64 v108, v110, v126, s[42:43]
	v_rcp_f32_e32 v6, v6
	v_rcp_f32_e32 v7, v7
	s_waitcnt lgkmcnt(0)
	v_cndmask_b32_e64 v11, v11, 0, s[44:45]
	v_cndmask_b32_e64 v109, v110, v122, s[40:41]
	v_cndmask_b32_e64 v116, v111, v127, s[42:43]
	v_pk_mul_f32 v[2:3], v[2:3], v[6:7]
	v_cndmask_b32_e64 v7, v142, v126, s[40:41]
	v_cndmask_b32_e64 v6, v142, v20, s[42:43]
	s_nop 0
	v_mov_b32_dpp v10, v7 row_ror:15 row_mask:0xf bank_mask:0xf
	v_cndmask_b32_e64 v7, v143, v21, s[42:43]
	v_mov_b32_dpp v6, v6 row_ror:1 row_mask:0xf bank_mask:0xf
	s_nop 0
	v_mov_b32_dpp v7, v7 row_ror:1 row_mask:0xf bank_mask:0xf
	v_cndmask_b32_e64 v20, v126, v142, s[42:43]
	s_waitcnt lgkmcnt(0)
	v_cndmask_b32_e64 v10, v10, 0, s[44:45]
	v_cndmask_b32_e64 v21, v126, v110, s[40:41]
	v_cndmask_b32_e64 v6, v6, 0, s[58:59]
	v_cndmask_b32_e64 v7, v7, 0, s[58:59]
	v_pk_fma_f32 v[6:7], v[4:5], v[6:7], v[136:137]
	v_mov_b32_dpp v20, v20 row_ror:1 row_mask:0xf bank_mask:0xf
	v_pk_fma_f32 v[6:7], v[8:9], v[10:11], v[6:7]
	v_mov_b32_dpp v21, v21 row_ror:15 row_mask:0xf bank_mask:0xf
	v_pk_add_f32 v[6:7], v[12:13], v[6:7]
	v_cndmask_b32_e64 v110, v122, v110, s[42:43]
	v_mul_f32_e32 v10, 0xbfb8aa3b, v6
	v_mul_f32_e32 v11, 0xbfb8aa3b, v7
	v_exp_f32_e32 v10, v10
	v_exp_f32_e32 v11, v11
	v_mov_b32_dpp v122, v16 row_ror:15 row_mask:0xf bank_mask:0xf
	v_cndmask_b32_e64 v16, v123, v111, s[42:43]
	v_cndmask_b32_e64 v117, v111, v123, s[40:41]
	v_pk_add_f32 v[10:11], v[10:11], 1.0 op_sel_hi:[1,0]
	v_mov_b32_dpp v111, v16 row_ror:1 row_mask:0xf bank_mask:0xf
	v_rcp_f32_e32 v10, v10
	v_rcp_f32_e32 v11, v11
	v_mov_b32_dpp v123, v17 row_ror:15 row_mask:0xf bank_mask:0xf
	v_cndmask_b32_e64 v17, v23, 0, s[46:47]
	s_waitcnt lgkmcnt(0)
	v_cndmask_b32_e64 v16, v21, 0, s[46:47]
	v_pk_mul_f32 v[6:7], v[6:7], v[10:11]
	v_cndmask_b32_e64 v11, v22, 0, s[48:49]
	v_cndmask_b32_e64 v10, v20, 0, s[48:49]
	v_pk_fma_f32 v[10:11], v[4:5], v[10:11], v[132:133]
	v_mov_b32_dpp v108, v108 row_ror:1 row_mask:0xf bank_mask:0xf
	v_pk_fma_f32 v[10:11], v[8:9], v[16:17], v[10:11]
	v_mov_b32_dpp v116, v116 row_ror:1 row_mask:0xf bank_mask:0xf
	v_pk_add_f32 v[10:11], v[12:13], v[10:11]
	v_mov_b32_dpp v109, v109 row_ror:15 row_mask:0xf bank_mask:0xf
	v_mul_f32_e32 v16, 0xbfb8aa3b, v10
	v_mul_f32_e32 v17, 0xbfb8aa3b, v11
	v_exp_f32_e32 v16, v16
	v_exp_f32_e32 v17, v17
	v_mov_b32_dpp v117, v117 row_ror:15 row_mask:0xf bank_mask:0xf
	s_waitcnt lgkmcnt(0)
	v_cndmask_b32_e64 v20, v109, 0, s[50:51]
	v_mov_b32_dpp v110, v110 row_ror:1 row_mask:0xf bank_mask:0xf
	v_pk_add_f32 v[16:17], v[16:17], 1.0 op_sel_hi:[1,0]
	v_cndmask_b32_e64 v23, v123, 0, s[56:57]
	v_rcp_f32_e32 v16, v16
	v_rcp_f32_e32 v17, v17
	v_cndmask_b32_e64 v21, v117, 0, s[50:51]
	v_cndmask_b32_e64 v22, v122, 0, s[56:57]
	v_pk_mul_f32 v[2:3], v[128:129], v[2:3]
	v_pk_mul_f32 v[10:11], v[10:11], v[16:17]
	v_cndmask_b32_e64 v17, v116, 0, s[52:53]
	v_cndmask_b32_e64 v16, v108, 0, s[52:53]
	v_pk_fma_f32 v[16:17], v[4:5], v[16:17], v[140:141]
	v_pk_mul_f32 v[6:7], v[134:135], v[6:7]
	v_pk_fma_f32 v[16:17], v[8:9], v[20:21], v[16:17]
	v_pk_mul_f32 v[10:11], v[118:119], v[10:11]
	v_pk_add_f32 v[16:17], v[12:13], v[16:17]
	s_nop 0
	v_mul_f32_e32 v20, 0xbfb8aa3b, v16
	v_mul_f32_e32 v21, 0xbfb8aa3b, v17
	v_exp_f32_e32 v20, v20
	v_exp_f32_e32 v21, v21
	s_nop 0
	v_pk_add_f32 v[20:21], v[20:21], 1.0 op_sel_hi:[1,0]
	s_nop 0
	v_rcp_f32_e32 v20, v20
	v_rcp_f32_e32 v21, v21
	s_nop 0
	v_pk_mul_f32 v[16:17], v[16:17], v[20:21]
	v_cndmask_b32_e64 v21, v111, 0, s[54:55]
	s_waitcnt lgkmcnt(0)
	v_cndmask_b32_e64 v20, v110, 0, s[54:55]
	v_pk_fma_f32 v[4:5], v[4:5], v[20:21], v[24:25]
	v_pk_mul_f32 v[16:17], v[102:103], v[16:17]
	v_pk_fma_f32 v[4:5], v[8:9], v[22:23], v[4:5]
	s_nop 0
	v_pk_add_f32 v[4:5], v[12:13], v[4:5]
	s_nop 0
	v_mul_f32_e32 v8, 0xbfb8aa3b, v4
	v_mul_f32_e32 v9, 0xbfb8aa3b, v5
	v_exp_f32_e32 v8, v8
	v_exp_f32_e32 v9, v9
	s_nop 0
	v_pk_add_f32 v[8:9], v[8:9], 1.0 op_sel_hi:[1,0]
	s_nop 0
	v_rcp_f32_e32 v8, v8
	v_rcp_f32_e32 v9, v9
	s_nop 0
	v_pk_mul_f32 v[4:5], v[4:5], v[8:9]
	v_add_u32_e32 v8, -1, v189
	v_cmp_gt_u32_e32 vcc, s0, v8
	v_cmp_gt_i32_e64 s[0:1], s10, v198
	v_pk_mul_f32 v[4:5], v[80:81], v[4:5]
	s_and_b64 s[58:59], vcc, s[0:1]
	s_and_saveexec_b64 s[0:1], s[58:59]
	s_cbranch_execz .LBB0_1350
	s_movk_i32 s58, 0xb00
	v_cvt_pk_bf16_f32 v14, v14, v15
	v_cvt_pk_bf16_f32 v15, v6, v7
	v_mul_lo_u32 v6, v198, s58
	v_cvt_pk_bf16_f32 v12, v82, v83
	v_cvt_pk_bf16_f32 v13, v90, v91
	v_add_lshl_u32 v6, v138, v6, 1
	global_store_dwordx4 v6, v[12:15], s[92:93]

.LBB0_1360:
	s_movk_i32 s0, 0x4000
	v_cmp_gt_i32_e32 vcc, s0, v190
	v_mov_b32_e32 v80, 0x100
	v_mov_b32_e32 v85, 0x400
	v_cndmask_b32_e32 v88, v202, v200, vcc
	v_and_b32_e32 v89, v88, v190
	v_cndmask_b32_e64 v80, 0, v80, s[44:45]
	v_mov_b32_e32 v83, 0x200
	v_cndmask_b32_e64 v84, 0, 4, s[52:53]
	v_cndmask_b32_e64 v85, 0, v85, s[50:51]
	v_cmp_eq_u32_e32 vcc, 0, v89
	v_cndmask_b32_e64 v81, 0, 2, s[48:49]
	v_cndmask_b32_e64 v83, 0, v83, s[46:47]
	v_cndmask_b32_e64 v90, 0, 16, vcc
	v_or3_b32 v80, v85, v80, v84
	v_cmp_gt_i32_e32 vcc, s0, v191
	v_or3_b32 v80, v80, v83, v81
	v_cndmask_b32_e64 v86, 0, 8, s[54:55]
	v_cndmask_b32_e32 v83, v202, v200, vcc
	v_and_b32_e32 v84, v83, v191
	v_cmp_eq_u32_e32 vcc, 0, v84
	v_cndmask_b32_e64 v87, 0, v201, s[56:57]
	v_cmp_eq_u32_e64 s[44:45], v89, v88
	v_cndmask_b32_e64 v85, 0, 32, vcc
	v_cmp_eq_u32_e32 vcc, v84, v83
	v_mov_b32_e32 v83, 0x2000
	v_mov_b32_e32 v88, 0x1000
	v_or3_b32 v80, v80, v86, v87
	v_cndmask_b32_e32 v83, 0, v83, vcc
	v_cndmask_b32_e64 v88, 0, v88, s[44:45]
	v_or_b32_e32 v81, v80, v90
	v_or_b32_e32 v83, v83, v85
	v_cmp_gt_i32_e32 vcc, s0, v193
	v_or3_b32 v83, v83, v88, v81
	v_mov_b32_e32 v86, 0x80
	v_cndmask_b32_e32 v81, v202, v200, vcc
	v_and_b32_e32 v84, v81, v193
	v_cmp_eq_u32_e32 vcc, 0, v84
	s_waitcnt lgkmcnt(0)
	v_cndmask_b32_e64 v18, v70, v18, s[42:43]
	v_cndmask_b32_e64 v19, v71, v19, s[42:43]
	v_cndmask_b32_e64 v85, 0, 64, vcc
	v_cmp_eq_u32_e32 vcc, v84, v81
	v_mov_b32_e32 v81, 0x4000
	v_mov_b32_dpp v18, v18 row_ror:1 row_mask:0xf bank_mask:0xf
	v_cndmask_b32_e32 v81, 0, v81, vcc
	v_cmp_gt_i32_e32 vcc, s0, v195
	v_or3_b32 v84, v81, v85, v83
	v_mov_b32_dpp v19, v19 row_ror:1 row_mask:0xf bank_mask:0xf
	v_cndmask_b32_e32 v81, v202, v200, vcc
	v_and_b32_e32 v85, v81, v195
	v_cmp_eq_u32_e32 vcc, 0, v85
	v_cndmask_b32_e64 v14, v120, v14, s[40:41]
	s_nop 1
	v_mov_b32_dpp v97, v14 row_ror:15 row_mask:0xf bank_mask:0xf
	v_cndmask_b32_e32 v86, 0, v86, vcc
	v_cmp_eq_u32_e32 vcc, v85, v81
	v_mov_b32_e32 v81, 0x8000
	v_cndmask_b32_e64 v14, v121, v105, s[42:43]
	v_cndmask_b32_e32 v81, 0, v81, vcc
	v_or3_b32 v86, v81, v86, v84
	v_cndmask_b32_e64 v81, v70, v78, s[40:41]
	s_nop 1
	v_mov_b32_dpp v85, v81 row_ror:15 row_mask:0xf bank_mask:0xf
	v_cndmask_b32_e64 v81, v71, v79, s[40:41]
	s_nop 1
	v_mov_b32_dpp v81, v81 row_ror:15 row_mask:0xf bank_mask:0xf
	v_mov_b32_dpp v102, v14 row_ror:1 row_mask:0xf bank_mask:0xf
	v_bitop3_b32 v14, v80, 16, v90 bitop3:0xc8
	v_cmp_eq_u32_e64 s[46:47], 0, v14
	v_cndmask_b32_e64 v87, v78, v70, s[42:43]
	v_cndmask_b32_e64 v89, v79, v71, s[42:43]
	s_waitcnt lgkmcnt(0)
	v_cndmask_b32_e64 v19, 0, v19, s[46:47]
	v_cndmask_b32_e64 v18, 0, v18, s[46:47]
	v_pk_mul_f32 v[70:71], v[70:71], v[22:23]
	v_cndmask_b32_e64 v81, v81, 0, s[44:45]
	v_cndmask_b32_e64 v80, v85, 0, s[44:45]
	v_pk_fma_f32 v[18:19], v[2:3], v[18:19], v[70:71]
	v_cndmask_b32_e64 v88, v78, v104, s[40:41]
	v_pk_fma_f32 v[18:19], v[6:7], v[80:81], v[18:19]
	v_mov_b32_dpp v87, v87 row_ror:1 row_mask:0xf bank_mask:0xf
	v_pk_add_f32 v[18:19], v[10:11], v[18:19]
	v_cndmask_b32_e64 v91, v79, v105, s[40:41]
	v_mul_f32_e32 v70, 0xbfb8aa3b, v18
	v_mul_f32_e32 v71, 0xbfb8aa3b, v19
	v_exp_f32_e32 v70, v70
	v_exp_f32_e32 v71, v71
	v_mov_b32_dpp v89, v89 row_ror:1 row_mask:0xf bank_mask:0xf
	v_mov_b32_dpp v88, v88 row_ror:15 row_mask:0xf bank_mask:0xf
	v_mov_b32_dpp v91, v91 row_ror:15 row_mask:0xf bank_mask:0xf
	v_pk_add_f32 v[70:71], v[70:71], 1.0 op_sel_hi:[1,0]
	v_cndmask_b32_e64 v92, v104, v78, s[42:43]
	v_rcp_f32_e32 v70, v70
	v_rcp_f32_e32 v71, v71
	v_cndmask_b32_e64 v94, v105, v79, s[42:43]
	v_pk_mul_f32 v[78:79], v[78:79], v[22:23]
	v_cndmask_b32_e64 v93, v104, v120, s[40:41]
	v_pk_mul_f32 v[18:19], v[18:19], v[70:71]
	v_mov_b32_dpp v92, v92 row_ror:1 row_mask:0xf bank_mask:0xf
	v_pk_mul_f32 v[66:67], v[66:67], v[18:19]
	v_and_b32_e32 v18, 32, v83
	v_cmp_eq_u32_e64 s[48:49], 0, v18
	v_and_b32_e32 v18, 0x2000, v83
	v_cmp_eq_u32_e64 s[50:51], 0, v18
	s_waitcnt lgkmcnt(0)
	v_cndmask_b32_e64 v71, 0, v89, s[48:49]
	v_cndmask_b32_e64 v70, 0, v87, s[48:49]
	v_cndmask_b32_e64 v81, 0, v91, s[50:51]
	v_cndmask_b32_e64 v80, 0, v88, s[50:51]
	v_pk_fma_f32 v[70:71], v[2:3], v[70:71], v[78:79]
	v_cndmask_b32_e64 v95, v105, v121, s[40:41]
	v_pk_fma_f32 v[70:71], v[6:7], v[80:81], v[70:71]
	v_mov_b32_dpp v94, v94 row_ror:1 row_mask:0xf bank_mask:0xf
	v_pk_add_f32 v[70:71], v[10:11], v[70:71]
	v_mov_b32_dpp v93, v93 row_ror:15 row_mask:0xf bank_mask:0xf
	v_mul_f32_e32 v78, 0xbfb8aa3b, v70
	v_mul_f32_e32 v79, 0xbfb8aa3b, v71
	v_exp_f32_e32 v78, v78
	v_exp_f32_e32 v79, v79
	v_mov_b32_dpp v95, v95 row_ror:15 row_mask:0xf bank_mask:0xf
	v_cndmask_b32_e64 v96, v120, v104, s[42:43]
	s_nop 1
	v_mov_b32_dpp v96, v96 row_ror:1 row_mask:0xf bank_mask:0xf
	v_pk_add_f32 v[78:79], v[78:79], 1.0 op_sel_hi:[1,0]
	v_cndmask_b32_e64 v15, v121, v15, s[40:41]
	v_rcp_f32_e32 v78, v78
	v_rcp_f32_e32 v79, v79
	v_mov_b32_dpp v103, v15 row_ror:15 row_mask:0xf bank_mask:0xf
	v_and_b32_e32 v83, 0x8000, v86
	v_cmp_eq_u32_e64 s[58:59], 0, v83
	v_pk_mul_f32 v[70:71], v[70:71], v[78:79]
	v_and_b32_e32 v78, 0x4000, v84
	v_pk_mul_f32 v[70:71], v[76:77], v[70:71]
	v_and_b32_e32 v76, 64, v84
	v_cmp_eq_u32_e64 s[52:53], 0, v76
	v_cmp_eq_u32_e64 s[54:55], 0, v78
	v_pk_mul_f32 v[84:85], v[104:105], v[22:23]
	s_waitcnt lgkmcnt(0)
	v_cndmask_b32_e64 v77, 0, v94, s[52:53]
	v_cndmask_b32_e64 v76, 0, v92, s[52:53]
	v_cndmask_b32_e64 v79, 0, v95, s[54:55]
	v_cndmask_b32_e64 v78, 0, v93, s[54:55]
	v_pk_fma_f32 v[76:77], v[2:3], v[76:77], v[84:85]
	v_pk_mul_f32 v[22:23], v[120:121], v[22:23]
	v_pk_fma_f32 v[76:77], v[6:7], v[78:79], v[76:77]
	v_cndmask_b32_e64 v85, 0, v103, s[58:59]
	v_pk_add_f32 v[76:77], v[10:11], v[76:77]
	v_cndmask_b32_e64 v84, 0, v97, s[58:59]
	v_mul_f32_e32 v78, 0xbfb8aa3b, v76
	v_mul_f32_e32 v79, 0xbfb8aa3b, v77
	v_exp_f32_e32 v78, v78
	v_exp_f32_e32 v79, v79
	v_pk_mul_f32 v[14:15], v[64:65], v[24:25]
	v_pk_mul_f32 v[18:19], v[68:69], v[24:25]
	v_pk_mul_f32 v[80:81], v[72:73], v[24:25]
	v_pk_add_f32 v[78:79], v[78:79], 1.0 op_sel_hi:[1,0]
	v_cndmask_b32_e64 v16, v112, v16, s[40:41]
	v_rcp_f32_e32 v78, v78
	v_rcp_f32_e32 v79, v79
	v_cndmask_b32_e64 v17, v113, v17, s[40:41]
	v_mov_b32_dpp v16, v16 row_ror:15 row_mask:0xf bank_mask:0xf
	s_nop 0
	v_mov_b32_dpp v17, v17 row_ror:15 row_mask:0xf bank_mask:0xf
	v_pk_mul_f32 v[76:77], v[76:77], v[78:79]
	v_and_b32_e32 v78, 0x80, v86
	v_cmp_eq_u32_e64 s[56:57], 0, v78
	v_pk_mul_f32 v[24:25], v[112:113], v[24:25]
	v_pk_mul_f32 v[76:77], v[100:101], v[76:77]
	v_cndmask_b32_e64 v79, 0, v102, s[56:57]
	v_cndmask_b32_e64 v78, 0, v96, s[56:57]
	v_pk_fma_f32 v[2:3], v[2:3], v[78:79], v[22:23]
	v_cndmask_b32_e64 v22, v72, v68, s[42:43]
	v_pk_fma_f32 v[2:3], v[6:7], v[84:85], v[2:3]
	v_cndmask_b32_e64 v23, v72, v112, s[40:41]
	v_pk_add_f32 v[2:3], v[10:11], v[2:3]
	v_cndmask_b32_e64 v10, v68, v64, s[42:43]
	v_mul_f32_e32 v6, 0xbfb8aa3b, v2
	v_mul_f32_e32 v7, 0xbfb8aa3b, v3
	v_exp_f32_e32 v6, v6
	v_exp_f32_e32 v7, v7
	v_cndmask_b32_e64 v11, v68, v72, s[40:41]
	v_mov_b32_dpp v10, v10 row_ror:1 row_mask:0xf bank_mask:0xf
	s_nop 0
	v_mov_b32_dpp v11, v11 row_ror:15 row_mask:0xf bank_mask:0xf
	v_pk_add_f32 v[6:7], v[6:7], 1.0 op_sel_hi:[1,0]
	v_mov_b32_dpp v22, v22 row_ror:1 row_mask:0xf bank_mask:0xf
	v_rcp_f32_e32 v6, v6
	v_rcp_f32_e32 v7, v7
	v_mov_b32_dpp v23, v23 row_ror:15 row_mask:0xf bank_mask:0xf
	s_and_b64 vcc, exec, s[60:61]
	v_pk_mul_f32 v[2:3], v[2:3], v[6:7]
	s_nop 0
	v_pk_mul_f32 v[78:79], v[114:115], v[2:3]
	v_cndmask_b32_e64 v3, v64, v68, s[40:41]
	v_cndmask_b32_e64 v2, v64, v20, s[42:43]
	s_nop 0
	v_mov_b32_dpp v6, v3 row_ror:15 row_mask:0xf bank_mask:0xf
	v_cndmask_b32_e64 v3, v65, v21, s[42:43]
	v_mov_b32_dpp v2, v2 row_ror:1 row_mask:0xf bank_mask:0xf
	v_cndmask_b32_e64 v7, v65, v69, s[40:41]
	v_mov_b32_dpp v3, v3 row_ror:1 row_mask:0xf bank_mask:0xf
	s_nop 0
	v_mov_b32_dpp v7, v7 row_ror:15 row_mask:0xf bank_mask:0xf
	s_waitcnt lgkmcnt(0)
	v_cndmask_b32_e64 v6, v6, 0, s[44:45]
	v_cndmask_b32_e64 v2, 0, v2, s[46:47]
	v_cndmask_b32_e64 v20, v69, v65, s[42:43]
	v_cndmask_b32_e64 v3, 0, v3, s[46:47]
	v_cndmask_b32_e64 v7, v7, 0, s[44:45]
	v_pk_fma_f32 v[2:3], v[4:5], v[2:3], v[14:15]
	v_cndmask_b32_e64 v21, v69, v73, s[40:41]
	v_pk_fma_f32 v[2:3], v[8:9], v[6:7], v[2:3]
	v_mov_b32_dpp v20, v20 row_ror:1 row_mask:0xf bank_mask:0xf
	v_pk_add_f32 v[2:3], v[12:13], v[2:3]
	v_mov_b32_dpp v21, v21 row_ror:15 row_mask:0xf bank_mask:0xf
	v_mul_f32_e32 v6, 0xbfb8aa3b, v2
	v_mul_f32_e32 v7, 0xbfb8aa3b, v3
	v_exp_f32_e32 v6, v6
	v_exp_f32_e32 v7, v7
	v_cndmask_b32_e64 v64, v73, v69, s[42:43]
	v_cndmask_b32_e64 v65, v73, v113, s[40:41]
	s_nop 0
	v_mov_b32_dpp v64, v64 row_ror:1 row_mask:0xf bank_mask:0xf
	v_pk_add_f32 v[6:7], v[6:7], 1.0 op_sel_hi:[1,0]
	v_mov_b32_dpp v65, v65 row_ror:15 row_mask:0xf bank_mask:0xf
	v_rcp_f32_e32 v6, v6
	v_rcp_f32_e32 v7, v7
	v_cndmask_b32_e64 v68, v112, v72, s[42:43]
	v_cndmask_b32_e64 v69, v113, v73, s[42:43]
	s_nop 0
	v_mov_b32_dpp v68, v68 row_ror:1 row_mask:0xf bank_mask:0xf
	v_pk_mul_f32 v[2:3], v[2:3], v[6:7]
	s_waitcnt lgkmcnt(0)
	v_cndmask_b32_e64 v7, 0, v21, s[50:51]
	v_pk_mul_f32 v[56:57], v[56:57], v[2:3]
	v_cndmask_b32_e64 v3, 0, v20, s[48:49]
	v_cndmask_b32_e64 v2, 0, v10, s[48:49]
	v_cndmask_b32_e64 v6, 0, v11, s[50:51]
	v_pk_fma_f32 v[2:3], v[4:5], v[2:3], v[18:19]
	v_mov_b32_dpp v69, v69 row_ror:1 row_mask:0xf bank_mask:0xf
	v_pk_fma_f32 v[2:3], v[8:9], v[6:7], v[2:3]
	v_mov_b32_e32 v14, 0
	v_pk_add_f32 v[2:3], v[12:13], v[2:3]
	v_mov_b32_e32 v18, 0
	v_mul_f32_e32 v6, 0xbfb8aa3b, v2
	v_mul_f32_e32 v7, 0xbfb8aa3b, v3
	v_exp_f32_e32 v6, v6
	v_exp_f32_e32 v7, v7
	v_mov_b32_e32 v19, 0
	v_mov_b32_e32 v20, 0
	v_mov_b32_e32 v21, 0
	v_pk_add_f32 v[6:7], v[6:7], 1.0 op_sel_hi:[1,0]
	s_nop 0
	v_rcp_f32_e32 v6, v6
	v_rcp_f32_e32 v7, v7
	s_nop 0
	v_pk_mul_f32 v[2:3], v[2:3], v[6:7]
	s_nop 0
	v_pk_mul_f32 v[54:55], v[54:55], v[2:3]
	v_cndmask_b32_e64 v3, 0, v64, s[52:53]
	v_cndmask_b32_e64 v2, 0, v22, s[52:53]
	v_cndmask_b32_e64 v7, 0, v65, s[54:55]
	v_cndmask_b32_e64 v6, 0, v23, s[54:55]
	v_pk_fma_f32 v[2:3], v[4:5], v[2:3], v[80:81]
	s_nop 0
	v_pk_fma_f32 v[2:3], v[8:9], v[6:7], v[2:3]
	s_nop 0
	v_pk_add_f32 v[2:3], v[12:13], v[2:3]
	s_nop 0
	v_mul_f32_e32 v6, 0xbfb8aa3b, v2
	v_mul_f32_e32 v7, 0xbfb8aa3b, v3
	v_exp_f32_e32 v6, v6
	v_exp_f32_e32 v7, v7
	s_nop 0
	v_pk_add_f32 v[6:7], v[6:7], 1.0 op_sel_hi:[1,0]
	s_nop 0
	v_rcp_f32_e32 v6, v6
	v_rcp_f32_e32 v7, v7
	s_nop 0
	v_pk_mul_f32 v[2:3], v[2:3], v[6:7]
	s_nop 0
	v_pk_mul_f32 v[62:63], v[62:63], v[2:3]
	s_waitcnt lgkmcnt(0)
	v_cndmask_b32_e64 v3, 0, v69, s[56:57]
	v_cndmask_b32_e64 v2, 0, v68, s[56:57]
	v_cndmask_b32_e64 v7, 0, v17, s[58:59]
	v_cndmask_b32_e64 v6, 0, v16, s[58:59]
	v_pk_fma_f32 v[2:3], v[4:5], v[2:3], v[24:25]
	s_nop 0
	v_pk_fma_f32 v[2:3], v[8:9], v[6:7], v[2:3]
	s_nop 0
	v_pk_add_f32 v[2:3], v[12:13], v[2:3]
	s_nop 0
	v_mul_f32_e32 v4, 0xbfb8aa3b, v2
	v_mul_f32_e32 v5, 0xbfb8aa3b, v3
	v_exp_f32_e32 v4, v4
	v_exp_f32_e32 v5, v5
	s_nop 0
	v_pk_add_f32 v[4:5], v[4:5], 1.0 op_sel_hi:[1,0]
	s_nop 0
	v_rcp_f32_e32 v4, v4
	v_rcp_f32_e32 v5, v5
	s_nop 0
	v_pk_mul_f32 v[2:3], v[2:3], v[4:5]
	s_nop 0
	v_pk_mul_f32 v[64:65], v[74:75], v[2:3]
	s_nop 0
	ds_read_b128 v[2:5], v219 offset:16
	ds_read_b128 v[22:25], v220 offset:16
	ds_read_b128 v[6:9], v221 offset:16
	ds_read_b128 v[10:13], v222 offset:16
	s_cbranch_vccnz .LBB0_1362
	ds_read_b128 v[18:21], v218 offset:1040

.LBB0_1364:
	s_waitcnt lgkmcnt(0)
	v_cndmask_b32_e64 v18, v58, v18, s[42:43]
	v_cndmask_b32_e64 v19, v59, v19, s[42:43]
	v_cndmask_b32_e64 v68, v58, v42, s[40:41]
	v_mov_b32_dpp v18, v18 row_ror:1 row_mask:0xf bank_mask:0xf
	v_cndmask_b32_e64 v69, v59, v43, s[40:41]
	v_mov_b32_dpp v19, v19 row_ror:1 row_mask:0xf bank_mask:0xf
	v_mov_b32_dpp v68, v68 row_ror:15 row_mask:0xf bank_mask:0xf
	v_mov_b32_dpp v69, v69 row_ror:15 row_mask:0xf bank_mask:0xf
	v_cndmask_b32_e64 v14, v48, v14, s[40:41]
	s_nop 1
	v_mov_b32_dpp v85, v14 row_ror:15 row_mask:0xf bank_mask:0xf
	v_cndmask_b32_e64 v14, v49, v39, s[42:43]
	v_cndmask_b32_e64 v15, v49, v15, s[40:41]
	v_cndmask_b32_e64 v72, v42, v58, s[42:43]
	v_cndmask_b32_e64 v74, v43, v59, s[42:43]
	v_mov_b32_dpp v86, v14 row_ror:1 row_mask:0xf bank_mask:0xf
	v_mov_b32_dpp v87, v15 row_ror:15 row_mask:0xf bank_mask:0xf
	s_waitcnt lgkmcnt(0)
	v_cndmask_b32_e64 v15, 0, v19, s[46:47]
	v_cndmask_b32_e64 v14, 0, v18, s[46:47]
	v_pk_mul_f32 v[58:59], v[58:59], v[22:23]
	v_cndmask_b32_e64 v19, v69, 0, s[44:45]
	v_cndmask_b32_e64 v18, v68, 0, s[44:45]
	v_pk_fma_f32 v[14:15], v[2:3], v[14:15], v[58:59]
	v_cndmask_b32_e64 v73, v42, v38, s[40:41]
	v_pk_fma_f32 v[14:15], v[6:7], v[18:19], v[14:15]
	v_mov_b32_dpp v72, v72 row_ror:1 row_mask:0xf bank_mask:0xf
	v_pk_add_f32 v[14:15], v[10:11], v[14:15]
	v_cndmask_b32_e64 v75, v43, v39, s[40:41]
	v_mul_f32_e32 v18, 0xbfb8aa3b, v14
	v_mul_f32_e32 v19, 0xbfb8aa3b, v15
	v_exp_f32_e32 v18, v18
	v_exp_f32_e32 v19, v19
	v_mov_b32_dpp v74, v74 row_ror:1 row_mask:0xf bank_mask:0xf
	v_mov_b32_dpp v73, v73 row_ror:15 row_mask:0xf bank_mask:0xf
	v_mov_b32_dpp v75, v75 row_ror:15 row_mask:0xf bank_mask:0xf
	v_pk_add_f32 v[18:19], v[18:19], 1.0 op_sel_hi:[1,0]
	v_cndmask_b32_e64 v80, v38, v42, s[42:43]
	v_rcp_f32_e32 v18, v18
	v_rcp_f32_e32 v19, v19
	v_cndmask_b32_e64 v82, v39, v43, s[42:43]
	v_pk_mul_f32 v[42:43], v[42:43], v[22:23]
	s_waitcnt lgkmcnt(0)
	v_cndmask_b32_e64 v59, 0, v75, s[50:51]
	v_pk_mul_f32 v[14:15], v[14:15], v[18:19]
	v_cndmask_b32_e64 v19, 0, v74, s[48:49]
	v_cndmask_b32_e64 v18, 0, v72, s[48:49]
	v_cndmask_b32_e64 v58, 0, v73, s[50:51]
	v_pk_fma_f32 v[18:19], v[2:3], v[18:19], v[42:43]
	v_cndmask_b32_e64 v81, v38, v48, s[40:41]
	v_pk_fma_f32 v[18:19], v[6:7], v[58:59], v[18:19]
	v_mov_b32_dpp v80, v80 row_ror:1 row_mask:0xf bank_mask:0xf
	v_pk_add_f32 v[18:19], v[10:11], v[18:19]
	v_cndmask_b32_e64 v83, v39, v49, s[40:41]
	v_mul_f32_e32 v42, 0xbfb8aa3b, v18
	v_mul_f32_e32 v43, 0xbfb8aa3b, v19
	v_exp_f32_e32 v42, v42
	v_exp_f32_e32 v43, v43
	v_mov_b32_dpp v82, v82 row_ror:1 row_mask:0xf bank_mask:0xf
	v_mov_b32_dpp v81, v81 row_ror:15 row_mask:0xf bank_mask:0xf
	v_mov_b32_dpp v83, v83 row_ror:15 row_mask:0xf bank_mask:0xf
	v_pk_add_f32 v[42:43], v[42:43], 1.0 op_sel_hi:[1,0]
	v_cndmask_b32_e64 v84, v48, v38, s[42:43]
	v_rcp_f32_e32 v42, v42
	v_rcp_f32_e32 v43, v43
	v_pk_mul_f32 v[38:39], v[38:39], v[22:23]
	v_mov_b32_dpp v84, v84 row_ror:1 row_mask:0xf bank_mask:0xf
	v_pk_mul_f32 v[22:23], v[48:49], v[22:23]
	v_pk_mul_f32 v[18:19], v[18:19], v[42:43]
	s_waitcnt lgkmcnt(0)
	v_cndmask_b32_e64 v43, 0, v83, s[54:55]
	v_pk_mul_f32 v[18:19], v[34:35], v[18:19]
	v_cndmask_b32_e64 v35, 0, v82, s[52:53]
	v_cndmask_b32_e64 v34, 0, v80, s[52:53]
	v_cndmask_b32_e64 v42, 0, v81, s[54:55]
	v_pk_fma_f32 v[34:35], v[2:3], v[34:35], v[38:39]
	v_pk_mul_f32 v[68:69], v[60:61], v[24:25]
	v_pk_fma_f32 v[34:35], v[6:7], v[42:43], v[34:35]
	v_cndmask_b32_e64 v16, v40, v16, s[40:41]
	v_pk_add_f32 v[34:35], v[10:11], v[34:35]
	v_pk_mul_f32 v[14:15], v[50:51], v[14:15]
	v_mul_f32_e32 v38, 0xbfb8aa3b, v34
	v_mul_f32_e32 v39, 0xbfb8aa3b, v35
	v_exp_f32_e32 v38, v38
	v_exp_f32_e32 v39, v39
	v_pk_mul_f32 v[50:51], v[44:45], v[24:25]
	v_pk_mul_f32 v[58:59], v[28:29], v[24:25]
	v_pk_mul_f32 v[24:25], v[40:41], v[24:25]
	v_pk_add_f32 v[38:39], v[38:39], 1.0 op_sel_hi:[1,0]
	v_cndmask_b32_e64 v17, v41, v17, s[40:41]
	v_rcp_f32_e32 v38, v38
	v_rcp_f32_e32 v39, v39
	s_movk_i32 s0, 0xfe
	v_pk_mul_f32 v[34:35], v[34:35], v[38:39]
	s_nop 0
	v_pk_mul_f32 v[32:33], v[32:33], v[34:35]
	v_cndmask_b32_e64 v35, 0, v86, s[56:57]
	v_cndmask_b32_e64 v34, 0, v84, s[56:57]
	v_cndmask_b32_e64 v39, 0, v87, s[58:59]
	v_cndmask_b32_e64 v38, 0, v85, s[58:59]
	v_pk_fma_f32 v[2:3], v[2:3], v[34:35], v[22:23]
	v_cndmask_b32_e64 v22, v45, v61, s[42:43]
	v_pk_fma_f32 v[2:3], v[6:7], v[38:39], v[2:3]
	v_cndmask_b32_e64 v23, v45, v29, s[40:41]
	v_pk_add_f32 v[2:3], v[10:11], v[2:3]
	v_cndmask_b32_e64 v11, v61, v45, s[40:41]
	v_mul_f32_e32 v6, 0xbfb8aa3b, v2
	v_mul_f32_e32 v7, 0xbfb8aa3b, v3
	v_exp_f32_e32 v6, v6
	v_exp_f32_e32 v7, v7
	v_mov_b32_dpp v11, v11 row_ror:15 row_mask:0xf bank_mask:0xf
	v_mov_b32_dpp v22, v22 row_ror:1 row_mask:0xf bank_mask:0xf
	v_mov_b32_dpp v23, v23 row_ror:15 row_mask:0xf bank_mask:0xf
	v_pk_add_f32 v[6:7], v[6:7], 1.0 op_sel_hi:[1,0]
	v_cndmask_b32_e64 v34, v28, v44, s[42:43]
	v_rcp_f32_e32 v6, v6
	v_rcp_f32_e32 v7, v7
	s_waitcnt lgkmcnt(0)
	v_cndmask_b32_e64 v11, v11, 0, s[44:45]
	v_cndmask_b32_e64 v35, v28, v40, s[40:41]
	v_cndmask_b32_e64 v38, v29, v45, s[42:43]
	v_pk_mul_f32 v[2:3], v[2:3], v[6:7]
	v_cndmask_b32_e64 v7, v60, v44, s[40:41]
	v_cndmask_b32_e64 v6, v60, v20, s[42:43]
	s_nop 0
	v_mov_b32_dpp v10, v7 row_ror:15 row_mask:0xf bank_mask:0xf
	v_cndmask_b32_e64 v7, v61, v21, s[42:43]
	v_mov_b32_dpp v6, v6 row_ror:1 row_mask:0xf bank_mask:0xf
	s_nop 0
	v_mov_b32_dpp v7, v7 row_ror:1 row_mask:0xf bank_mask:0xf
	v_cndmask_b32_e64 v20, v44, v60, s[42:43]
	s_waitcnt lgkmcnt(0)
	v_cndmask_b32_e64 v10, v10, 0, s[44:45]
	v_cndmask_b32_e64 v21, v44, v28, s[40:41]
	v_cndmask_b32_e64 v6, 0, v6, s[46:47]
	v_cndmask_b32_e64 v7, 0, v7, s[46:47]
	v_pk_fma_f32 v[6:7], v[4:5], v[6:7], v[68:69]
	v_mov_b32_dpp v20, v20 row_ror:1 row_mask:0xf bank_mask:0xf
	v_pk_fma_f32 v[6:7], v[8:9], v[10:11], v[6:7]
	v_mov_b32_dpp v21, v21 row_ror:15 row_mask:0xf bank_mask:0xf
	v_pk_add_f32 v[6:7], v[12:13], v[6:7]
	v_cndmask_b32_e64 v28, v40, v28, s[42:43]
	v_mul_f32_e32 v10, 0xbfb8aa3b, v6
	v_mul_f32_e32 v11, 0xbfb8aa3b, v7
	v_exp_f32_e32 v10, v10
	v_exp_f32_e32 v11, v11
	v_mov_b32_dpp v40, v16 row_ror:15 row_mask:0xf bank_mask:0xf
	v_cndmask_b32_e64 v16, v41, v29, s[42:43]
	v_cndmask_b32_e64 v39, v29, v41, s[40:41]
	v_pk_add_f32 v[10:11], v[10:11], 1.0 op_sel_hi:[1,0]
	v_mov_b32_dpp v29, v16 row_ror:1 row_mask:0xf bank_mask:0xf
	v_rcp_f32_e32 v10, v10
	v_rcp_f32_e32 v11, v11
	v_mov_b32_dpp v41, v17 row_ror:15 row_mask:0xf bank_mask:0xf
	v_cndmask_b32_e64 v17, 0, v23, s[50:51]
	s_waitcnt lgkmcnt(0)
	v_cndmask_b32_e64 v16, 0, v21, s[50:51]
	v_pk_mul_f32 v[6:7], v[6:7], v[10:11]
	v_cndmask_b32_e64 v11, 0, v22, s[48:49]
	v_cndmask_b32_e64 v10, 0, v20, s[48:49]
	v_pk_fma_f32 v[10:11], v[4:5], v[10:11], v[50:51]
	v_mov_b32_dpp v34, v34 row_ror:1 row_mask:0xf bank_mask:0xf
	v_pk_fma_f32 v[10:11], v[8:9], v[16:17], v[10:11]
	v_mov_b32_dpp v38, v38 row_ror:1 row_mask:0xf bank_mask:0xf
	v_pk_add_f32 v[10:11], v[12:13], v[10:11]
	v_mov_b32_dpp v35, v35 row_ror:15 row_mask:0xf bank_mask:0xf
	v_mul_f32_e32 v16, 0xbfb8aa3b, v10
	v_mul_f32_e32 v17, 0xbfb8aa3b, v11
	v_exp_f32_e32 v16, v16
	v_exp_f32_e32 v17, v17
	v_mov_b32_dpp v39, v39 row_ror:15 row_mask:0xf bank_mask:0xf
	s_waitcnt lgkmcnt(0)
	v_cndmask_b32_e64 v20, 0, v35, s[54:55]
	v_mov_b32_dpp v28, v28 row_ror:1 row_mask:0xf bank_mask:0xf
	v_pk_add_f32 v[16:17], v[16:17], 1.0 op_sel_hi:[1,0]
	v_cndmask_b32_e64 v23, 0, v41, s[58:59]
	v_rcp_f32_e32 v16, v16
	v_rcp_f32_e32 v17, v17
	v_cndmask_b32_e64 v21, 0, v39, s[54:55]
	v_cndmask_b32_e64 v22, 0, v40, s[58:59]
	v_pk_mul_f32 v[2:3], v[46:47], v[2:3]
	v_pk_mul_f32 v[10:11], v[10:11], v[16:17]
	v_cndmask_b32_e64 v17, 0, v38, s[52:53]
	v_cndmask_b32_e64 v16, 0, v34, s[52:53]
	v_pk_fma_f32 v[16:17], v[4:5], v[16:17], v[58:59]
	v_pk_mul_f32 v[6:7], v[52:53], v[6:7]
	v_pk_fma_f32 v[16:17], v[8:9], v[20:21], v[16:17]
	v_pk_mul_f32 v[10:11], v[36:37], v[10:11]
	v_pk_add_f32 v[16:17], v[12:13], v[16:17]
	s_nop 0
	v_mul_f32_e32 v20, 0xbfb8aa3b, v16
	v_mul_f32_e32 v21, 0xbfb8aa3b, v17
	v_exp_f32_e32 v20, v20
	v_exp_f32_e32 v21, v21
	s_nop 0
	v_pk_add_f32 v[20:21], v[20:21], 1.0 op_sel_hi:[1,0]
	s_nop 0
	v_rcp_f32_e32 v20, v20
	v_rcp_f32_e32 v21, v21
	s_nop 0
	v_pk_mul_f32 v[16:17], v[16:17], v[20:21]
	v_cndmask_b32_e64 v21, 0, v29, s[56:57]
	s_waitcnt lgkmcnt(0)
	v_cndmask_b32_e64 v20, 0, v28, s[56:57]
	v_pk_fma_f32 v[4:5], v[4:5], v[20:21], v[24:25]
	v_pk_mul_f32 v[16:17], v[26:27], v[16:17]
	v_pk_fma_f32 v[4:5], v[8:9], v[22:23], v[4:5]
	s_nop 0
	v_pk_add_f32 v[4:5], v[12:13], v[4:5]
	s_nop 0
	v_mul_f32_e32 v8, 0xbfb8aa3b, v4
	v_mul_f32_e32 v9, 0xbfb8aa3b, v5
	v_exp_f32_e32 v8, v8
	v_exp_f32_e32 v9, v9
	s_nop 0
	v_pk_add_f32 v[8:9], v[8:9], 1.0 op_sel_hi:[1,0]
	s_nop 0
	v_rcp_f32_e32 v8, v8
	v_rcp_f32_e32 v9, v9
	s_nop 0
	v_pk_mul_f32 v[4:5], v[4:5], v[8:9]
	v_add_u32_e32 v8, 0x7f, v189
	v_cmp_gt_u32_e32 vcc, s0, v8
	v_cmp_gt_i32_e64 s[0:1], s10, v190
	v_pk_mul_f32 v[4:5], v[30:31], v[4:5]
	s_and_b64 s[40:41], vcc, s[0:1]
	s_and_saveexec_b64 s[0:1], s[40:41]
	s_cbranch_execz .LBB0_1366
	s_movk_i32 s40, 0xb00
	v_cvt_pk_bf16_f32 v14, v14, v15
	v_cvt_pk_bf16_f32 v15, v6, v7
	v_mul_lo_u32 v6, v190, s40
	v_cvt_pk_bf16_f32 v12, v66, v67
	v_cvt_pk_bf16_f32 v13, v56, v57
	v_add_lshl_u32 v6, v138, v6, 1
	global_store_dwordx4 v6, v[12:15], s[92:93]
